# SP1 load segments: relocated A-half-0 DMAs issued after the first 8 ds_reads (before the A-fragment reads); vmcnt 8/6/8/6
# speedup vs baseline: 1.0028x; 1.0028x over previous
; #define PG8_STAGE(bufoff, gbase, voff) do { _Pragma("unroll") for (int _i = 0; _i < 2; ++_i) \
;         __builtin_amdgcn_global_load_lds((const unsigned*)((const char*)(gbase) + (voff)[_i]), (PG8_LAS unsigned*)(lds + (bufoff) + ldsw + _i * 8192), 16, 0, 0); } while (0)
; #define PG8_LDA(dst, b, h) do { _Pragma("unroll") for (int m = 0; m < 4; ++m) _Pragma("unroll") for (int k = 0; k < 2; ++k) dst[m][k] = *(const PG8_LAS bf16x8*)(lds + PG8_SA(b, h) + aoff + m * 2048 + k * 1024); } while (0)
; #define PG8_LDB(dst, b, h) do { _Pragma("unroll") for (int n = 0; n < 2; ++n) _Pragma("unroll") for (int k = 0; k < 2; ++k) dst[n][k] = *(const PG8_LAS bf16x8*)(lds + PG8_SB(b, h) + boff + n * 2048 + k * 1024); } while (0)
; #define PG8_MMA(ai, bj, At, Bt) do { __builtin_amdgcn_s_setprio(1); _Pragma("unroll") for (int m = 0; m < 4; ++m) _Pragma("unroll") for (int n = 0; n < 2; ++n) _Pragma("unroll") for (int k = 0; k < 2; ++k) \
;         acc[ai][bj][m][n] = __builtin_amdgcn_mfma_f32_16x16x32_bf16(Bt[n][k], At[m][k], acc[ai][bj][m][n], 0, 0, 0); __builtin_amdgcn_s_setprio(0); } while (0)
; #define PG8_WAIT_V(n) asm volatile("s_waitcnt vmcnt(" #n ")" ::: "memory")
; #define PG8_WAIT_L(n) asm volatile("s_waitcnt lgkmcnt(" #n ")" ::: "memory")
; #define PG8_BAR __builtin_amdgcn_s_barrier()
; #define PG8_SCHED __builtin_amdgcn_sched_barrier(0)
; template <class Epi, class Sched, bool ALIGN_EPI = false, bool SP2 = false>
; __device__ __forceinline__ void gemm_phase(PG8_LAS unsigned char* lds, const Gemm g, const Sched& S, const Epi& E) {
;     ...
;             PG8_LDB(B0, 0, 0); PG8_LDB(B1, 0, 1); PG8_SCHED; PG8_LDA(At, 0, 0); PG8_STAGE(PG8_SA(1, 1), a1 + hstep, voffA);
;             PG8_WAIT_V(8); PG8_WAIT_L(0); PG8_BAR; PG8_MMA(0, 0, At, B0); PG8_MMA(0, 1, At, B1); PG8_BAR; PG8_SCHED;
;             PG8_LDA(At, 0, 1); PG8_STAGE(PG8_SB(0, 0), b2, voffB); PG8_STAGE(PG8_SB(0, 1), b2 + hstep, voffB); PG8_STAGE(PG8_SA(0, 0), a2, voffA);
;             PG8_WAIT_V(8); PG8_WAIT_L(0); PG8_BAR; PG8_MMA(1, 0, At, B0); PG8_MMA(1, 1, At, B1); PG8_BAR; PG8_SCHED;
.LBB0_150:
	ds_read_b128 v[144:147], v155
	ds_read_b128 v[148:151], v155 offset:1024
	ds_read_b128 v[160:163], v155 offset:2048
	ds_read_b128 v[164:167], v155 offset:3072
	ds_read_b128 v[168:171], v156
	ds_read_b128 v[172:175], v156 offset:1024
	ds_read_b128 v[176:179], v156 offset:2048
	ds_read_b128 v[180:183], v156 offset:3072
	s_mov_b32 m0, s48
	s_nop 0
	global_load_lds_dwordx4 v[250:251], off
	s_mov_b32 m0, s49
	s_nop 0
	global_load_lds_dwordx4 v[252:253], off
	s_add_u32 s30, s28, 0xfff80080
	s_addc_u32 s31, s29, -1
	s_cmp_eq_u32 s60, 28
	s_cselect_b32 s35, s15, s31
	s_cselect_b32 s34, s56, s30
	s_cselect_b32 s31, s13, s59
	s_cselect_b32 s30, s57, s58
	v_lshl_add_u64 v[216:217], s[28:29], 0, v[136:137]
	s_add_i32 m0, s25, 0xc000
	ds_read_b128 v[184:187], v157
	ds_read_b128 v[188:191], v157 offset:1024
	ds_read_b128 v[192:195], v157 offset:2048
	ds_read_b128 v[196:199], v157 offset:3072
	ds_read_b128 v[200:203], v157 offset:4096
	ds_read_b128 v[204:207], v157 offset:5120
	ds_read_b128 v[208:211], v157 offset:6144
	ds_read_b128 v[212:215], v157 offset:7168
	global_load_lds_dwordx4 v[216:217], off
	v_lshl_add_u64 v[216:217], s[28:29], 0, v[138:139]
	s_add_i32 m0, s25, 0xe000
	s_nop 0
	global_load_lds_dwordx4 v[216:217], off
	s_waitcnt vmcnt(8)
	s_waitcnt lgkmcnt(0)
	s_barrier
	s_waitcnt lgkmcnt(0)
	v_mfma_f32_16x16x32_bf16 v[124:127], v[144:147], v[184:187], v[124:127]
	v_mfma_f32_16x16x32_bf16 v[120:123], v[160:163], v[184:187], v[120:123]
	s_add_u32 s62, s30, 0x80000
	v_mfma_f32_16x16x32_bf16 v[108:111], v[144:147], v[192:195], v[108:111]
	v_mfma_f32_16x16x32_bf16 v[104:107], v[160:163], v[192:195], v[104:107]
	s_addc_u32 s63, s31, 0
	v_mfma_f32_16x16x32_bf16 v[92:95], v[144:147], v[200:203], v[92:95]
	v_mfma_f32_16x16x32_bf16 v[88:91], v[160:163], v[200:203], v[88:91]
	v_lshl_add_u64 v[216:217], s[30:31], 0, v[132:133]
	v_mfma_f32_16x16x32_bf16 v[76:79], v[144:147], v[208:211], v[76:79]
	v_mfma_f32_16x16x32_bf16 v[72:75], v[160:163], v[208:211], v[72:75]
	v_lshl_add_u64 v[218:219], s[30:31], 0, v[128:129]
	v_mfma_f32_16x16x32_bf16 v[124:127], v[148:151], v[188:191], v[124:127]
	v_mfma_f32_16x16x32_bf16 v[120:123], v[164:167], v[188:191], v[120:123]
	v_lshl_add_u64 v[246:247], s[62:63], 0, v[132:133]
	v_mfma_f32_16x16x32_bf16 v[108:111], v[148:151], v[196:199], v[108:111]
	v_mfma_f32_16x16x32_bf16 v[104:107], v[164:167], v[196:199], v[104:107]
	v_lshl_add_u64 v[222:223], s[34:35], 0, v[130:131]
	v_mfma_f32_16x16x32_bf16 v[92:95], v[148:151], v[204:207], v[92:95]
	v_mfma_f32_16x16x32_bf16 v[88:91], v[164:167], v[204:207], v[88:91]
	v_lshl_add_u64 v[248:249], s[62:63], 0, v[128:129]
	v_mfma_f32_16x16x32_bf16 v[76:79], v[148:151], v[212:215], v[76:79]
	v_mfma_f32_16x16x32_bf16 v[72:75], v[164:167], v[212:215], v[72:75]
	v_lshl_add_u64 v[220:221], s[34:35], 0, v[134:135]
	v_mfma_f32_16x16x32_bf16 v[116:119], v[168:171], v[184:187], v[116:119]
	v_mfma_f32_16x16x32_bf16 v[112:115], v[176:179], v[184:187], v[112:115]
	v_mfma_f32_16x16x32_bf16 v[100:103], v[168:171], v[192:195], v[100:103]
	v_mfma_f32_16x16x32_bf16 v[96:99], v[176:179], v[192:195], v[96:99]
	v_mfma_f32_16x16x32_bf16 v[84:87], v[168:171], v[200:203], v[84:87]
	v_mfma_f32_16x16x32_bf16 v[80:83], v[176:179], v[200:203], v[80:83]
	v_mfma_f32_16x16x32_bf16 v[68:71], v[168:171], v[208:211], v[68:71]
	v_mfma_f32_16x16x32_bf16 v[64:67], v[176:179], v[208:211], v[64:67]
	v_mfma_f32_16x16x32_bf16 v[116:119], v[172:175], v[188:191], v[116:119]
	v_mfma_f32_16x16x32_bf16 v[112:115], v[180:183], v[188:191], v[112:115]
	v_mfma_f32_16x16x32_bf16 v[100:103], v[172:175], v[196:199], v[100:103]
	v_mfma_f32_16x16x32_bf16 v[96:99], v[180:183], v[196:199], v[96:99]
	v_mfma_f32_16x16x32_bf16 v[84:87], v[172:175], v[204:207], v[84:87]
	v_mfma_f32_16x16x32_bf16 v[80:83], v[180:183], v[204:207], v[80:83]
	v_mfma_f32_16x16x32_bf16 v[68:71], v[172:175], v[212:215], v[68:71]
	v_mfma_f32_16x16x32_bf16 v[64:67], v[180:183], v[212:215], v[64:67]
	s_add_i32 s61, s52, s42
	s_mov_b32 m0, s61
	s_barrier
	global_load_lds_dwordx4 v[216:217], off
	s_add_i32 m0, s61, 0x2000
	s_add_i32 s61, s53, s42
	global_load_lds_dwordx4 v[218:219], off
	s_mov_b32 m0, s61
	s_nop 0
	global_load_lds_dwordx4 v[246:247], off
	s_add_i32 m0, s61, 0x2000
	s_nop 0
	global_load_lds_dwordx4 v[248:249], off
	ds_read_b128 v[184:187], v157 offset:16384
	ds_read_b128 v[188:191], v157 offset:17408
	ds_read_b128 v[192:195], v157 offset:18432
	ds_read_b128 v[196:199], v157 offset:19456
	ds_read_b128 v[200:203], v157 offset:20480
	ds_read_b128 v[204:207], v157 offset:21504
	ds_read_b128 v[208:211], v157 offset:22528
	ds_read_b128 v[212:215], v157 offset:23552
	s_waitcnt vmcnt(6)
	s_waitcnt lgkmcnt(0)
	s_barrier
; #define PG8_STAGE(bufoff, gbase, voff) do { _Pragma("unroll") for (int _i = 0; _i < 2; ++_i) \
;         __builtin_amdgcn_global_load_lds((const unsigned*)((const char*)(gbase) + (voff)[_i]), (PG8_LAS unsigned*)(lds + (bufoff) + ldsw + _i * 8192), 16, 0, 0); } while (0)
; #define PG8_LDA(dst, b, h) do { _Pragma("unroll") for (int m = 0; m < 4; ++m) _Pragma("unroll") for (int k = 0; k < 2; ++k) dst[m][k] = *(const PG8_LAS bf16x8*)(lds + PG8_SA(b, h) + aoff + m * 2048 + k * 1024); } while (0)
; #define PG8_LDB(dst, b, h) do { _Pragma("unroll") for (int n = 0; n < 2; ++n) _Pragma("unroll") for (int k = 0; k < 2; ++k) dst[n][k] = *(const PG8_LAS bf16x8*)(lds + PG8_SB(b, h) + boff + n * 2048 + k * 1024); } while (0)
; #define PG8_MMA(ai, bj, At, Bt) do { __builtin_amdgcn_s_setprio(1); _Pragma("unroll") for (int m = 0; m < 4; ++m) _Pragma("unroll") for (int n = 0; n < 2; ++n) _Pragma("unroll") for (int k = 0; k < 2; ++k) \
;         acc[ai][bj][m][n] = __builtin_amdgcn_mfma_f32_16x16x32_bf16(Bt[n][k], At[m][k], acc[ai][bj][m][n], 0, 0, 0); __builtin_amdgcn_s_setprio(0); } while (0)
; #define PG8_WAIT_V(n) asm volatile("s_waitcnt vmcnt(" #n ")" ::: "memory")
; #define PG8_WAIT_L(n) asm volatile("s_waitcnt lgkmcnt(" #n ")" ::: "memory")
; #define PG8_BAR __builtin_amdgcn_s_barrier()
; #define PG8_SCHED __builtin_amdgcn_sched_barrier(0)
; template <class Epi, class Sched, bool ALIGN_EPI = false, bool SP2 = false>
; __device__ __forceinline__ void gemm_phase(PG8_LAS unsigned char* lds, const Gemm g, const Sched& S, const Epi& E) {
;     ...
;             PG8_WAIT_V(8); PG8_WAIT_L(0); PG8_BAR; PG8_MMA(1, 0, At, B0); PG8_MMA(1, 1, At, B1); PG8_BAR; PG8_SCHED;
;             PG8_LDB(B0, 1, 0); PG8_LDB(B1, 1, 1); PG8_SCHED; PG8_LDA(At, 1, 0); PG8_STAGE(PG8_SA(0, 1), a2 + hstep, voffA);
;             PG8_WAIT_V(8); PG8_WAIT_L(0); PG8_BAR; PG8_MMA(0, 0, At, B0); PG8_MMA(0, 1, At, B1); PG8_BAR; PG8_SCHED;
	s_waitcnt lgkmcnt(0)
	v_mfma_f32_16x16x32_bf16 v[60:63], v[144:147], v[184:187], v[60:63]
	v_mfma_f32_16x16x32_bf16 v[56:59], v[160:163], v[184:187], v[56:59]
	v_mfma_f32_16x16x32_bf16 v[44:47], v[144:147], v[192:195], v[44:47]
	v_mfma_f32_16x16x32_bf16 v[40:43], v[160:163], v[192:195], v[40:43]
	v_mfma_f32_16x16x32_bf16 v[28:31], v[144:147], v[200:203], v[28:31]
	v_mfma_f32_16x16x32_bf16 v[24:27], v[160:163], v[200:203], v[24:27]
	v_mfma_f32_16x16x32_bf16 v[12:15], v[144:147], v[208:211], v[12:15]
	v_mfma_f32_16x16x32_bf16 v[8:11], v[160:163], v[208:211], v[8:11]
	v_mfma_f32_16x16x32_bf16 v[60:63], v[148:151], v[188:191], v[60:63]
	v_mfma_f32_16x16x32_bf16 v[56:59], v[164:167], v[188:191], v[56:59]
	v_mfma_f32_16x16x32_bf16 v[44:47], v[148:151], v[196:199], v[44:47]
	v_mfma_f32_16x16x32_bf16 v[40:43], v[164:167], v[196:199], v[40:43]
	v_mfma_f32_16x16x32_bf16 v[28:31], v[148:151], v[204:207], v[28:31]
	v_mfma_f32_16x16x32_bf16 v[24:27], v[164:167], v[204:207], v[24:27]
	v_mfma_f32_16x16x32_bf16 v[12:15], v[148:151], v[212:215], v[12:15]
	v_mfma_f32_16x16x32_bf16 v[8:11], v[164:167], v[212:215], v[8:11]
	v_mfma_f32_16x16x32_bf16 v[52:55], v[168:171], v[184:187], v[52:55]
	v_mfma_f32_16x16x32_bf16 v[48:51], v[176:179], v[184:187], v[48:51]
	v_mfma_f32_16x16x32_bf16 v[36:39], v[168:171], v[192:195], v[36:39]
	v_mfma_f32_16x16x32_bf16 v[32:35], v[176:179], v[192:195], v[32:35]
	v_mfma_f32_16x16x32_bf16 v[20:23], v[168:171], v[200:203], v[20:23]
	v_mfma_f32_16x16x32_bf16 v[16:19], v[176:179], v[200:203], v[16:19]
	v_mfma_f32_16x16x32_bf16 v[4:7], v[168:171], v[208:211], v[4:7]
	v_mfma_f32_16x16x32_bf16 v[0:3], v[176:179], v[208:211], v[0:3]
	v_mfma_f32_16x16x32_bf16 v[52:55], v[172:175], v[188:191], v[52:55]
	v_mfma_f32_16x16x32_bf16 v[48:51], v[180:183], v[188:191], v[48:51]
	v_mfma_f32_16x16x32_bf16 v[36:39], v[172:175], v[196:199], v[36:39]
	v_mfma_f32_16x16x32_bf16 v[32:35], v[180:183], v[196:199], v[32:35]
	v_mfma_f32_16x16x32_bf16 v[20:23], v[172:175], v[204:207], v[20:23]
	v_mfma_f32_16x16x32_bf16 v[16:19], v[180:183], v[204:207], v[16:19]
	v_mfma_f32_16x16x32_bf16 v[4:7], v[172:175], v[212:215], v[4:7]
	v_mfma_f32_16x16x32_bf16 v[0:3], v[180:183], v[212:215], v[0:3]
	s_barrier
	s_add_i32 s61, 0, 0x18000
	s_add_i32 s62, 0, 0x1c000
	v_add_u32_e32 v164, s61, v153
	v_add_u32_e32 v180, s62, v153
	ds_read_b128 v[144:147], v164
	ds_read_b128 v[148:151], v164 offset:1024
	ds_read_b128 v[160:163], v164 offset:2048
	ds_read_b128 v[164:167], v164 offset:3072
	ds_read_b128 v[168:171], v180
	ds_read_b128 v[172:175], v180 offset:1024
	ds_read_b128 v[176:179], v180 offset:2048
	ds_read_b128 v[180:183], v180 offset:3072
	s_mov_b32 m0, s25
	s_nop 0
	global_load_lds_dwordx4 v[220:221], off
	s_mov_b32 m0, s45
	s_nop 0
	global_load_lds_dwordx4 v[222:223], off
	s_add_u32 s34, s34, 0x80000
	s_addc_u32 s35, s35, 0
	s_mov_b32 m0, s46
	v_lshl_add_u64 v[224:225], s[34:35], 0, v[134:135]
	ds_read_b128 v[184:187], v157 offset:32768
	ds_read_b128 v[188:191], v157 offset:33792
	ds_read_b128 v[192:195], v157 offset:34816
	ds_read_b128 v[196:199], v157 offset:35840
	ds_read_b128 v[200:203], v157 offset:36864
	ds_read_b128 v[204:207], v157 offset:37888
	ds_read_b128 v[208:211], v157 offset:38912
	ds_read_b128 v[212:215], v157 offset:39936
	global_load_lds_dwordx4 v[224:225], off
	v_lshl_add_u64 v[224:225], s[34:35], 0, v[130:131]
	s_mov_b32 m0, s47
	s_nop 0
	global_load_lds_dwordx4 v[224:225], off
	s_waitcnt vmcnt(8)
	s_waitcnt lgkmcnt(0)
	s_barrier
; #define PG8_STAGE(bufoff, gbase, voff) do { _Pragma("unroll") for (int _i = 0; _i < 2; ++_i) \
;         __builtin_amdgcn_global_load_lds((const unsigned*)((const char*)(gbase) + (voff)[_i]), (PG8_LAS unsigned*)(lds + (bufoff) + ldsw + _i * 8192), 16, 0, 0); } while (0)
; #define PG8_LDA(dst, b, h) do { _Pragma("unroll") for (int m = 0; m < 4; ++m) _Pragma("unroll") for (int k = 0; k < 2; ++k) dst[m][k] = *(const PG8_LAS bf16x8*)(lds + PG8_SA(b, h) + aoff + m * 2048 + k * 1024); } while (0)
; #define PG8_MMA(ai, bj, At, Bt) do { __builtin_amdgcn_s_setprio(1); _Pragma("unroll") for (int m = 0; m < 4; ++m) _Pragma("unroll") for (int n = 0; n < 2; ++n) _Pragma("unroll") for (int k = 0; k < 2; ++k) \
;         acc[ai][bj][m][n] = __builtin_amdgcn_mfma_f32_16x16x32_bf16(Bt[n][k], At[m][k], acc[ai][bj][m][n], 0, 0, 0); __builtin_amdgcn_s_setprio(0); } while (0)
; #define PG8_WAIT_V(n) asm volatile("s_waitcnt vmcnt(" #n ")" ::: "memory")
; #define PG8_WAIT_L(n) asm volatile("s_waitcnt lgkmcnt(" #n ")" ::: "memory")
; #define PG8_BAR __builtin_amdgcn_s_barrier()
; #define PG8_SCHED __builtin_amdgcn_sched_barrier(0)
; template <class Epi, class Sched, bool ALIGN_EPI = false, bool SP2 = false>
; __device__ __forceinline__ void gemm_phase(PG8_LAS unsigned char* lds, const Gemm g, const Sched& S, const Epi& E) {
;     ...
;         for (int t = 0; t < nt; t += 2) {
;     ...
;             PG8_WAIT_V(8); PG8_WAIT_L(0); PG8_BAR; PG8_MMA(0, 0, At, B0); PG8_MMA(0, 1, At, B1); PG8_BAR; PG8_SCHED;
;             PG8_LDA(At, 1, 1); PG8_STAGE(PG8_SB(1, 0), b3, voffB); PG8_STAGE(PG8_SB(1, 1), b3 + hstep, voffB); PG8_STAGE(PG8_SA(1, 0), a3, voffA);
;             PG8_WAIT_V(8); PG8_WAIT_L(0); PG8_BAR; PG8_MMA(1, 0, At, B0); PG8_MMA(1, 1, At, B1); PG8_BAR; PG8_SCHED;
	s_waitcnt lgkmcnt(0)
	v_mfma_f32_16x16x32_bf16 v[124:127], v[144:147], v[184:187], v[124:127]
	v_mfma_f32_16x16x32_bf16 v[120:123], v[160:163], v[184:187], v[120:123]
	s_add_u32 s30, s30, 0x80080
	v_mfma_f32_16x16x32_bf16 v[108:111], v[144:147], v[192:195], v[108:111]
	v_mfma_f32_16x16x32_bf16 v[104:107], v[160:163], v[192:195], v[104:107]
	s_addc_u32 s31, s31, 0
	v_mfma_f32_16x16x32_bf16 v[92:95], v[144:147], v[200:203], v[92:95]
	v_mfma_f32_16x16x32_bf16 v[88:91], v[160:163], v[200:203], v[88:91]
	v_lshl_add_u64 v[216:217], v[216:217], 0, s[8:9]
	v_mfma_f32_16x16x32_bf16 v[76:79], v[144:147], v[208:211], v[76:79]
	v_mfma_f32_16x16x32_bf16 v[72:75], v[160:163], v[208:211], v[72:75]
	v_lshl_add_u64 v[218:219], v[218:219], 0, s[8:9]
	v_mfma_f32_16x16x32_bf16 v[124:127], v[148:151], v[188:191], v[124:127]
	v_mfma_f32_16x16x32_bf16 v[120:123], v[164:167], v[188:191], v[120:123]
	v_lshl_add_u64 v[246:247], s[30:31], 0, v[132:133]
	v_mfma_f32_16x16x32_bf16 v[108:111], v[148:151], v[196:199], v[108:111]
	v_mfma_f32_16x16x32_bf16 v[104:107], v[164:167], v[196:199], v[104:107]
	v_lshl_add_u64 v[248:249], s[30:31], 0, v[128:129]
	v_mfma_f32_16x16x32_bf16 v[92:95], v[148:151], v[204:207], v[92:95]
	v_mfma_f32_16x16x32_bf16 v[88:91], v[164:167], v[204:207], v[88:91]
	v_lshl_add_u64 v[250:251], v[220:221], 0, s[8:9]
	v_mfma_f32_16x16x32_bf16 v[76:79], v[148:151], v[212:215], v[76:79]
	v_mfma_f32_16x16x32_bf16 v[72:75], v[164:167], v[212:215], v[72:75]
	v_lshl_add_u64 v[252:253], v[222:223], 0, s[8:9]
	v_mfma_f32_16x16x32_bf16 v[116:119], v[168:171], v[184:187], v[116:119]
	v_mfma_f32_16x16x32_bf16 v[112:115], v[176:179], v[184:187], v[112:115]
	v_mfma_f32_16x16x32_bf16 v[100:103], v[168:171], v[192:195], v[100:103]
	v_mfma_f32_16x16x32_bf16 v[96:99], v[176:179], v[192:195], v[96:99]
	v_mfma_f32_16x16x32_bf16 v[84:87], v[168:171], v[200:203], v[84:87]
	v_mfma_f32_16x16x32_bf16 v[80:83], v[176:179], v[200:203], v[80:83]
	v_mfma_f32_16x16x32_bf16 v[68:71], v[168:171], v[208:211], v[68:71]
	v_mfma_f32_16x16x32_bf16 v[64:67], v[176:179], v[208:211], v[64:67]
	v_mfma_f32_16x16x32_bf16 v[116:119], v[172:175], v[188:191], v[116:119]
	v_mfma_f32_16x16x32_bf16 v[112:115], v[180:183], v[188:191], v[112:115]
	v_mfma_f32_16x16x32_bf16 v[100:103], v[172:175], v[196:199], v[100:103]
	v_mfma_f32_16x16x32_bf16 v[96:99], v[180:183], v[196:199], v[96:99]
	v_mfma_f32_16x16x32_bf16 v[84:87], v[172:175], v[204:207], v[84:87]
	v_mfma_f32_16x16x32_bf16 v[80:83], v[180:183], v[204:207], v[80:83]
	v_mfma_f32_16x16x32_bf16 v[68:71], v[172:175], v[212:215], v[68:71]
	v_mfma_f32_16x16x32_bf16 v[64:67], v[180:183], v[212:215], v[64:67]
	s_add_i32 s34, s61, s42
	s_mov_b32 m0, s34
	s_barrier
	global_load_lds_dwordx4 v[216:217], off
	s_add_i32 m0, s34, 0x2000
	s_add_i32 s34, s62, s42
	global_load_lds_dwordx4 v[218:219], off
	s_mov_b32 m0, s34
	s_nop 0
	global_load_lds_dwordx4 v[246:247], off
	s_add_i32 m0, s34, 0x2000
	s_nop 0
	global_load_lds_dwordx4 v[248:249], off
	ds_read_b128 v[184:187], v157 offset:49152
	ds_read_b128 v[188:191], v157 offset:50176
	ds_read_b128 v[192:195], v157 offset:51200
	ds_read_b128 v[196:199], v157 offset:52224
	ds_read_b128 v[200:203], v157 offset:53248
	ds_read_b128 v[204:207], v157 offset:54272
	ds_read_b128 v[208:211], v157 offset:55296
	ds_read_b128 v[212:215], v157 offset:56320
	s_waitcnt vmcnt(6)
	s_waitcnt lgkmcnt(0)
	s_barrier
	s_waitcnt lgkmcnt(0)
	v_mfma_f32_16x16x32_bf16 v[60:63], v[144:147], v[184:187], v[60:63]
	v_mfma_f32_16x16x32_bf16 v[56:59], v[160:163], v[184:187], v[56:59]
	v_mfma_f32_16x16x32_bf16 v[44:47], v[144:147], v[192:195], v[44:47]
	v_mfma_f32_16x16x32_bf16 v[40:43], v[160:163], v[192:195], v[40:43]
	v_mfma_f32_16x16x32_bf16 v[28:31], v[144:147], v[200:203], v[28:31]
	v_mfma_f32_16x16x32_bf16 v[24:27], v[160:163], v[200:203], v[24:27]
	v_mfma_f32_16x16x32_bf16 v[12:15], v[144:147], v[208:211], v[12:15]
	v_mfma_f32_16x16x32_bf16 v[8:11], v[160:163], v[208:211], v[8:11]
	v_mfma_f32_16x16x32_bf16 v[60:63], v[148:151], v[188:191], v[60:63]
	v_mfma_f32_16x16x32_bf16 v[56:59], v[164:167], v[188:191], v[56:59]
	v_mfma_f32_16x16x32_bf16 v[44:47], v[148:151], v[196:199], v[44:47]
	v_mfma_f32_16x16x32_bf16 v[40:43], v[164:167], v[196:199], v[40:43]
	v_mfma_f32_16x16x32_bf16 v[28:31], v[148:151], v[204:207], v[28:31]
	v_mfma_f32_16x16x32_bf16 v[24:27], v[164:167], v[204:207], v[24:27]
	v_mfma_f32_16x16x32_bf16 v[12:15], v[148:151], v[212:215], v[12:15]
	v_mfma_f32_16x16x32_bf16 v[8:11], v[164:167], v[212:215], v[8:11]
	v_mfma_f32_16x16x32_bf16 v[52:55], v[168:171], v[184:187], v[52:55]
	v_mfma_f32_16x16x32_bf16 v[48:51], v[176:179], v[184:187], v[48:51]
	v_mfma_f32_16x16x32_bf16 v[36:39], v[168:171], v[192:195], v[36:39]
	v_mfma_f32_16x16x32_bf16 v[32:35], v[176:179], v[192:195], v[32:35]
	s_add_i32 s60, s60, 2
	v_mfma_f32_16x16x32_bf16 v[20:23], v[168:171], v[200:203], v[20:23]
	v_mfma_f32_16x16x32_bf16 v[16:19], v[176:179], v[200:203], v[16:19]
	s_add_u32 s28, s28, 0x100
	v_mfma_f32_16x16x32_bf16 v[4:7], v[168:171], v[208:211], v[4:7]
	v_mfma_f32_16x16x32_bf16 v[0:3], v[176:179], v[208:211], v[0:3]
	s_addc_u32 s29, s29, 0
	v_mfma_f32_16x16x32_bf16 v[52:55], v[172:175], v[188:191], v[52:55]
	v_mfma_f32_16x16x32_bf16 v[48:51], v[180:183], v[188:191], v[48:51]
	s_add_u32 s58, s58, 0x100
	v_mfma_f32_16x16x32_bf16 v[36:39], v[172:175], v[196:199], v[36:39]
	v_mfma_f32_16x16x32_bf16 v[32:35], v[180:183], v[196:199], v[32:35]
	s_addc_u32 s59, s59, 0
	v_mfma_f32_16x16x32_bf16 v[20:23], v[172:175], v[204:207], v[20:23]
	v_mfma_f32_16x16x32_bf16 v[16:19], v[180:183], v[204:207], v[16:19]
	v_mfma_f32_16x16x32_bf16 v[4:7], v[172:175], v[212:215], v[4:7]
	v_mfma_f32_16x16x32_bf16 v[0:3], v[180:183], v[212:215], v[0:3]
	s_barrier
	s_cmp_gt_u32 s60, 29
	s_cbranch_scc0 .LBB0_150
	s_and_b64 vcc, exec, s[10:11]
	s_cbranch_vccz .LBB0_153
	s_barrier

; #define PG8_STAGE(bufoff, gbase, voff) do { _Pragma("unroll") for (int _i = 0; _i < 2; ++_i) \
;         __builtin_amdgcn_global_load_lds((const unsigned*)((const char*)(gbase) + (voff)[_i]), (PG8_LAS unsigned*)(lds + (bufoff) + ldsw + _i * 8192), 16, 0, 0); } while (0)
; #define PG8_LDA(dst, b, h) do { _Pragma("unroll") for (int m = 0; m < 4; ++m) _Pragma("unroll") for (int k = 0; k < 2; ++k) dst[m][k] = *(const PG8_LAS bf16x8*)(lds + PG8_SA(b, h) + aoff + m * 2048 + k * 1024); } while (0)
; #define PG8_LDB(dst, b, h) do { _Pragma("unroll") for (int n = 0; n < 2; ++n) _Pragma("unroll") for (int k = 0; k < 2; ++k) dst[n][k] = *(const PG8_LAS bf16x8*)(lds + PG8_SB(b, h) + boff + n * 2048 + k * 1024); } while (0)
; #define PG8_MMA(ai, bj, At, Bt) do { __builtin_amdgcn_s_setprio(1); _Pragma("unroll") for (int m = 0; m < 4; ++m) _Pragma("unroll") for (int n = 0; n < 2; ++n) _Pragma("unroll") for (int k = 0; k < 2; ++k) \
;         acc[ai][bj][m][n] = __builtin_amdgcn_mfma_f32_16x16x32_bf16(Bt[n][k], At[m][k], acc[ai][bj][m][n], 0, 0, 0); __builtin_amdgcn_s_setprio(0); } while (0)
; #define PG8_WAIT_V(n) asm volatile("s_waitcnt vmcnt(" #n ")" ::: "memory")
; #define PG8_WAIT_L(n) asm volatile("s_waitcnt lgkmcnt(" #n ")" ::: "memory")
; #define PG8_BAR __builtin_amdgcn_s_barrier()
; #define PG8_SCHED __builtin_amdgcn_sched_barrier(0)
; template <class Epi, class Sched, bool ALIGN_EPI = false, bool SP2 = false>
; __device__ __forceinline__ void gemm_phase(PG8_LAS unsigned char* lds, const Gemm g, const Sched& S, const Epi& E) {
;     ...
;             PG8_LDB(B0, 0, 0); PG8_LDB(B1, 0, 1); PG8_SCHED; PG8_LDA(At, 0, 0); PG8_STAGE(PG8_SA(1, 1), a1 + hstep, voffA);
;             PG8_WAIT_V(8); PG8_WAIT_L(0); PG8_BAR; PG8_MMA(0, 0, At, B0); PG8_MMA(0, 1, At, B1); PG8_BAR; PG8_SCHED;
;             PG8_LDA(At, 0, 1); PG8_STAGE(PG8_SB(0, 0), b2, voffB); PG8_STAGE(PG8_SB(0, 1), b2 + hstep, voffB); PG8_STAGE(PG8_SA(0, 0), a2, voffA);
;             PG8_WAIT_V(8); PG8_WAIT_L(0); PG8_BAR; PG8_MMA(1, 0, At, B0); PG8_MMA(1, 1, At, B1); PG8_BAR; PG8_SCHED;
.LBB0_621:
	ds_read_b128 v[128:131], v189
	ds_read_b128 v[132:135], v189 offset:1024
	ds_read_b128 v[136:139], v189 offset:2048
	ds_read_b128 v[140:143], v189 offset:3072
	ds_read_b128 v[144:147], v190
	ds_read_b128 v[148:151], v190 offset:1024
	ds_read_b128 v[168:171], v190 offset:2048
	ds_read_b128 v[172:175], v190 offset:3072
	s_mov_b32 m0, s50
	s_nop 0
	global_load_lds_dwordx4 v[250:251], off
	s_mov_b32 m0, s51
	s_nop 0
	global_load_lds_dwordx4 v[252:253], off
	s_add_u32 s36, s34, 0xfff80080
	s_addc_u32 s37, s35, -1
	s_cmp_eq_u32 s60, 28
	s_cselect_b32 s39, s17, s37
	s_cselect_b32 s38, s29, s36
	s_cselect_b32 s37, s15, s59
	s_cselect_b32 s36, s57, s58
	v_lshl_add_u64 v[184:185], s[34:35], 0, v[160:161]
	s_add_i32 m0, s31, 0xc000
	ds_read_b128 v[176:179], v191
	ds_read_b128 v[180:183], v191 offset:1024
	ds_read_b128 v[192:195], v191 offset:2048
	ds_read_b128 v[196:199], v191 offset:3072
	ds_read_b128 v[200:203], v191 offset:4096
	ds_read_b128 v[204:207], v191 offset:5120
	ds_read_b128 v[208:211], v191 offset:6144
	ds_read_b128 v[212:215], v191 offset:7168
	global_load_lds_dwordx4 v[184:185], off
	v_lshl_add_u64 v[184:185], s[34:35], 0, v[162:163]
	s_add_i32 m0, s31, 0xe000
	s_nop 0
	global_load_lds_dwordx4 v[184:185], off
	s_waitcnt vmcnt(8)
	s_waitcnt lgkmcnt(0)
	s_barrier
	s_waitcnt lgkmcnt(0)
	v_mfma_f32_16x16x32_bf16 v[124:127], v[128:131], v[176:179], v[124:127]
	v_mfma_f32_16x16x32_bf16 v[120:123], v[136:139], v[176:179], v[120:123]
	s_add_u32 s62, s36, 0x80000
	v_mfma_f32_16x16x32_bf16 v[108:111], v[128:131], v[192:195], v[108:111]
	v_mfma_f32_16x16x32_bf16 v[104:107], v[136:139], v[192:195], v[104:107]
	s_addc_u32 s63, s37, 0
	v_mfma_f32_16x16x32_bf16 v[92:95], v[128:131], v[200:203], v[92:95]
	v_mfma_f32_16x16x32_bf16 v[88:91], v[136:139], v[200:203], v[88:91]
	v_lshl_add_u64 v[184:185], s[36:37], 0, v[154:155]
	v_mfma_f32_16x16x32_bf16 v[76:79], v[128:131], v[208:211], v[76:79]
	v_mfma_f32_16x16x32_bf16 v[72:75], v[136:139], v[208:211], v[72:75]
	v_lshl_add_u64 v[216:217], s[36:37], 0, v[158:159]
	v_mfma_f32_16x16x32_bf16 v[124:127], v[132:135], v[180:183], v[124:127]
	v_mfma_f32_16x16x32_bf16 v[120:123], v[140:143], v[180:183], v[120:123]
	v_lshl_add_u64 v[246:247], s[62:63], 0, v[154:155]
	v_mfma_f32_16x16x32_bf16 v[108:111], v[132:135], v[196:199], v[108:111]
	v_mfma_f32_16x16x32_bf16 v[104:107], v[140:143], v[196:199], v[104:107]
	v_lshl_add_u64 v[220:221], s[38:39], 0, v[156:157]
	v_mfma_f32_16x16x32_bf16 v[92:95], v[132:135], v[204:207], v[92:95]
	v_mfma_f32_16x16x32_bf16 v[88:91], v[140:143], v[204:207], v[88:91]
	v_lshl_add_u64 v[248:249], s[62:63], 0, v[158:159]
	v_mfma_f32_16x16x32_bf16 v[76:79], v[132:135], v[212:215], v[76:79]
	v_mfma_f32_16x16x32_bf16 v[72:75], v[140:143], v[212:215], v[72:75]
	v_lshl_add_u64 v[218:219], s[38:39], 0, v[152:153]
	v_mfma_f32_16x16x32_bf16 v[116:119], v[144:147], v[176:179], v[116:119]
	v_mfma_f32_16x16x32_bf16 v[112:115], v[168:171], v[176:179], v[112:115]
	v_mfma_f32_16x16x32_bf16 v[100:103], v[144:147], v[192:195], v[100:103]
	v_mfma_f32_16x16x32_bf16 v[96:99], v[168:171], v[192:195], v[96:99]
	v_mfma_f32_16x16x32_bf16 v[84:87], v[144:147], v[200:203], v[84:87]
	v_mfma_f32_16x16x32_bf16 v[80:83], v[168:171], v[200:203], v[80:83]
	v_mfma_f32_16x16x32_bf16 v[68:71], v[144:147], v[208:211], v[68:71]
	v_mfma_f32_16x16x32_bf16 v[64:67], v[168:171], v[208:211], v[64:67]
	v_mfma_f32_16x16x32_bf16 v[116:119], v[148:151], v[180:183], v[116:119]
	v_mfma_f32_16x16x32_bf16 v[112:115], v[172:175], v[180:183], v[112:115]
	v_mfma_f32_16x16x32_bf16 v[100:103], v[148:151], v[196:199], v[100:103]
	v_mfma_f32_16x16x32_bf16 v[96:99], v[172:175], v[196:199], v[96:99]
	v_mfma_f32_16x16x32_bf16 v[84:87], v[148:151], v[204:207], v[84:87]
	v_mfma_f32_16x16x32_bf16 v[80:83], v[172:175], v[204:207], v[80:83]
	v_mfma_f32_16x16x32_bf16 v[68:71], v[148:151], v[212:215], v[68:71]
	v_mfma_f32_16x16x32_bf16 v[64:67], v[172:175], v[212:215], v[64:67]
	s_add_i32 s61, s54, s45
	s_mov_b32 m0, s61
	s_barrier
	global_load_lds_dwordx4 v[184:185], off
	s_add_i32 m0, s61, 0x2000
	s_add_i32 s61, s55, s45
	global_load_lds_dwordx4 v[216:217], off
	s_mov_b32 m0, s61
	s_nop 0
	global_load_lds_dwordx4 v[246:247], off
	s_add_i32 m0, s61, 0x2000
	s_nop 0
	global_load_lds_dwordx4 v[248:249], off
	ds_read_b128 v[176:179], v191 offset:16384
	ds_read_b128 v[180:183], v191 offset:17408
	ds_read_b128 v[192:195], v191 offset:18432
	ds_read_b128 v[196:199], v191 offset:19456
	ds_read_b128 v[200:203], v191 offset:20480
	ds_read_b128 v[204:207], v191 offset:21504
	ds_read_b128 v[208:211], v191 offset:22528
	ds_read_b128 v[212:215], v191 offset:23552
	s_waitcnt vmcnt(6)
	s_waitcnt lgkmcnt(0)
	s_barrier
; #define PG8_STAGE(bufoff, gbase, voff) do { _Pragma("unroll") for (int _i = 0; _i < 2; ++_i) \
;         __builtin_amdgcn_global_load_lds((const unsigned*)((const char*)(gbase) + (voff)[_i]), (PG8_LAS unsigned*)(lds + (bufoff) + ldsw + _i * 8192), 16, 0, 0); } while (0)
; #define PG8_LDA(dst, b, h) do { _Pragma("unroll") for (int m = 0; m < 4; ++m) _Pragma("unroll") for (int k = 0; k < 2; ++k) dst[m][k] = *(const PG8_LAS bf16x8*)(lds + PG8_SA(b, h) + aoff + m * 2048 + k * 1024); } while (0)
; #define PG8_LDB(dst, b, h) do { _Pragma("unroll") for (int n = 0; n < 2; ++n) _Pragma("unroll") for (int k = 0; k < 2; ++k) dst[n][k] = *(const PG8_LAS bf16x8*)(lds + PG8_SB(b, h) + boff + n * 2048 + k * 1024); } while (0)
; #define PG8_MMA(ai, bj, At, Bt) do { __builtin_amdgcn_s_setprio(1); _Pragma("unroll") for (int m = 0; m < 4; ++m) _Pragma("unroll") for (int n = 0; n < 2; ++n) _Pragma("unroll") for (int k = 0; k < 2; ++k) \
;         acc[ai][bj][m][n] = __builtin_amdgcn_mfma_f32_16x16x32_bf16(Bt[n][k], At[m][k], acc[ai][bj][m][n], 0, 0, 0); __builtin_amdgcn_s_setprio(0); } while (0)
; #define PG8_WAIT_V(n) asm volatile("s_waitcnt vmcnt(" #n ")" ::: "memory")
; #define PG8_WAIT_L(n) asm volatile("s_waitcnt lgkmcnt(" #n ")" ::: "memory")
; #define PG8_BAR __builtin_amdgcn_s_barrier()
; #define PG8_SCHED __builtin_amdgcn_sched_barrier(0)
; template <class Epi, class Sched, bool ALIGN_EPI = false, bool SP2 = false>
; __device__ __forceinline__ void gemm_phase(PG8_LAS unsigned char* lds, const Gemm g, const Sched& S, const Epi& E) {
;     ...
;             PG8_WAIT_V(8); PG8_WAIT_L(0); PG8_BAR; PG8_MMA(1, 0, At, B0); PG8_MMA(1, 1, At, B1); PG8_BAR; PG8_SCHED;
;             PG8_LDB(B0, 1, 0); PG8_LDB(B1, 1, 1); PG8_SCHED; PG8_LDA(At, 1, 0); PG8_STAGE(PG8_SA(0, 1), a2 + hstep, voffA);
;             PG8_WAIT_V(8); PG8_WAIT_L(0); PG8_BAR; PG8_MMA(0, 0, At, B0); PG8_MMA(0, 1, At, B1); PG8_BAR; PG8_SCHED;
	s_waitcnt lgkmcnt(0)
	v_mfma_f32_16x16x32_bf16 v[60:63], v[128:131], v[176:179], v[60:63]
	v_mfma_f32_16x16x32_bf16 v[56:59], v[136:139], v[176:179], v[56:59]
	v_mfma_f32_16x16x32_bf16 v[44:47], v[128:131], v[192:195], v[44:47]
	v_mfma_f32_16x16x32_bf16 v[40:43], v[136:139], v[192:195], v[40:43]
	v_mfma_f32_16x16x32_bf16 v[28:31], v[128:131], v[200:203], v[28:31]
	v_mfma_f32_16x16x32_bf16 v[24:27], v[136:139], v[200:203], v[24:27]
	v_mfma_f32_16x16x32_bf16 v[12:15], v[128:131], v[208:211], v[12:15]
	v_mfma_f32_16x16x32_bf16 v[8:11], v[136:139], v[208:211], v[8:11]
	v_mfma_f32_16x16x32_bf16 v[60:63], v[132:135], v[180:183], v[60:63]
	v_mfma_f32_16x16x32_bf16 v[56:59], v[140:143], v[180:183], v[56:59]
	v_mfma_f32_16x16x32_bf16 v[44:47], v[132:135], v[196:199], v[44:47]
	v_mfma_f32_16x16x32_bf16 v[40:43], v[140:143], v[196:199], v[40:43]
	v_mfma_f32_16x16x32_bf16 v[28:31], v[132:135], v[204:207], v[28:31]
	v_mfma_f32_16x16x32_bf16 v[24:27], v[140:143], v[204:207], v[24:27]
	v_mfma_f32_16x16x32_bf16 v[12:15], v[132:135], v[212:215], v[12:15]
	v_mfma_f32_16x16x32_bf16 v[8:11], v[140:143], v[212:215], v[8:11]
	v_mfma_f32_16x16x32_bf16 v[52:55], v[144:147], v[176:179], v[52:55]
	v_mfma_f32_16x16x32_bf16 v[48:51], v[168:171], v[176:179], v[48:51]
	v_mfma_f32_16x16x32_bf16 v[36:39], v[144:147], v[192:195], v[36:39]
	v_mfma_f32_16x16x32_bf16 v[32:35], v[168:171], v[192:195], v[32:35]
	v_mfma_f32_16x16x32_bf16 v[20:23], v[144:147], v[200:203], v[20:23]
	v_mfma_f32_16x16x32_bf16 v[16:19], v[168:171], v[200:203], v[16:19]
	v_mfma_f32_16x16x32_bf16 v[4:7], v[144:147], v[208:211], v[4:7]
	v_mfma_f32_16x16x32_bf16 v[0:3], v[168:171], v[208:211], v[0:3]
	v_mfma_f32_16x16x32_bf16 v[52:55], v[148:151], v[180:183], v[52:55]
	v_mfma_f32_16x16x32_bf16 v[48:51], v[172:175], v[180:183], v[48:51]
	v_mfma_f32_16x16x32_bf16 v[36:39], v[148:151], v[196:199], v[36:39]
	v_mfma_f32_16x16x32_bf16 v[32:35], v[172:175], v[196:199], v[32:35]
	v_mfma_f32_16x16x32_bf16 v[20:23], v[148:151], v[204:207], v[20:23]
	v_mfma_f32_16x16x32_bf16 v[16:19], v[172:175], v[204:207], v[16:19]
	v_mfma_f32_16x16x32_bf16 v[4:7], v[148:151], v[212:215], v[4:7]
	v_mfma_f32_16x16x32_bf16 v[0:3], v[172:175], v[212:215], v[0:3]
	s_barrier
	s_add_i32 s61, 0, 0x18000
	s_add_i32 s62, 0, 0x1c000
	v_add_u32_e32 v140, s61, v187
	v_add_u32_e32 v172, s62, v187
	ds_read_b128 v[128:131], v140
	ds_read_b128 v[132:135], v140 offset:1024
	ds_read_b128 v[136:139], v140 offset:2048
	ds_read_b128 v[140:143], v140 offset:3072
	ds_read_b128 v[144:147], v172
	ds_read_b128 v[148:151], v172 offset:1024
	ds_read_b128 v[168:171], v172 offset:2048
	ds_read_b128 v[172:175], v172 offset:3072
	s_mov_b32 m0, s31
	s_nop 0
	global_load_lds_dwordx4 v[218:219], off
	s_mov_b32 m0, s46
	s_nop 0
	global_load_lds_dwordx4 v[220:221], off
	s_add_u32 s38, s38, 0x80000
	s_addc_u32 s39, s39, 0
	s_mov_b32 m0, s47
	v_lshl_add_u64 v[222:223], s[38:39], 0, v[152:153]
	ds_read_b128 v[176:179], v191 offset:32768
	ds_read_b128 v[180:183], v191 offset:33792
	ds_read_b128 v[192:195], v191 offset:34816
	ds_read_b128 v[196:199], v191 offset:35840
	ds_read_b128 v[200:203], v191 offset:36864
	ds_read_b128 v[204:207], v191 offset:37888
	ds_read_b128 v[208:211], v191 offset:38912
	ds_read_b128 v[212:215], v191 offset:39936
	global_load_lds_dwordx4 v[222:223], off
	v_lshl_add_u64 v[222:223], s[38:39], 0, v[156:157]
	s_mov_b32 m0, s48
	s_nop 0
	global_load_lds_dwordx4 v[222:223], off
	s_waitcnt vmcnt(8)
	s_waitcnt lgkmcnt(0)
	s_barrier
; #define PG8_STAGE(bufoff, gbase, voff) do { _Pragma("unroll") for (int _i = 0; _i < 2; ++_i) \
;         __builtin_amdgcn_global_load_lds((const unsigned*)((const char*)(gbase) + (voff)[_i]), (PG8_LAS unsigned*)(lds + (bufoff) + ldsw + _i * 8192), 16, 0, 0); } while (0)
; #define PG8_LDA(dst, b, h) do { _Pragma("unroll") for (int m = 0; m < 4; ++m) _Pragma("unroll") for (int k = 0; k < 2; ++k) dst[m][k] = *(const PG8_LAS bf16x8*)(lds + PG8_SA(b, h) + aoff + m * 2048 + k * 1024); } while (0)
; #define PG8_MMA(ai, bj, At, Bt) do { __builtin_amdgcn_s_setprio(1); _Pragma("unroll") for (int m = 0; m < 4; ++m) _Pragma("unroll") for (int n = 0; n < 2; ++n) _Pragma("unroll") for (int k = 0; k < 2; ++k) \
;         acc[ai][bj][m][n] = __builtin_amdgcn_mfma_f32_16x16x32_bf16(Bt[n][k], At[m][k], acc[ai][bj][m][n], 0, 0, 0); __builtin_amdgcn_s_setprio(0); } while (0)
; #define PG8_WAIT_V(n) asm volatile("s_waitcnt vmcnt(" #n ")" ::: "memory")
; #define PG8_WAIT_L(n) asm volatile("s_waitcnt lgkmcnt(" #n ")" ::: "memory")
; #define PG8_BAR __builtin_amdgcn_s_barrier()
; #define PG8_SCHED __builtin_amdgcn_sched_barrier(0)
; template <class Epi, class Sched, bool ALIGN_EPI = false, bool SP2 = false>
; __device__ __forceinline__ void gemm_phase(PG8_LAS unsigned char* lds, const Gemm g, const Sched& S, const Epi& E) {
;     ...
;         for (int t = 0; t < nt; t += 2) {
;     ...
;             PG8_WAIT_V(8); PG8_WAIT_L(0); PG8_BAR; PG8_MMA(0, 0, At, B0); PG8_MMA(0, 1, At, B1); PG8_BAR; PG8_SCHED;
;             PG8_LDA(At, 1, 1); PG8_STAGE(PG8_SB(1, 0), b3, voffB); PG8_STAGE(PG8_SB(1, 1), b3 + hstep, voffB); PG8_STAGE(PG8_SA(1, 0), a3, voffA);
;             PG8_WAIT_V(8); PG8_WAIT_L(0); PG8_BAR; PG8_MMA(1, 0, At, B0); PG8_MMA(1, 1, At, B1); PG8_BAR; PG8_SCHED;
	s_waitcnt lgkmcnt(0)
	v_mfma_f32_16x16x32_bf16 v[124:127], v[128:131], v[176:179], v[124:127]
	v_mfma_f32_16x16x32_bf16 v[120:123], v[136:139], v[176:179], v[120:123]
	s_add_u32 s36, s36, 0x80080
	v_mfma_f32_16x16x32_bf16 v[108:111], v[128:131], v[192:195], v[108:111]
	v_mfma_f32_16x16x32_bf16 v[104:107], v[136:139], v[192:195], v[104:107]
	s_addc_u32 s37, s37, 0
	v_mfma_f32_16x16x32_bf16 v[92:95], v[128:131], v[200:203], v[92:95]
	v_mfma_f32_16x16x32_bf16 v[88:91], v[136:139], v[200:203], v[88:91]
	v_lshl_add_u64 v[184:185], v[184:185], 0, s[10:11]
	v_mfma_f32_16x16x32_bf16 v[76:79], v[128:131], v[208:211], v[76:79]
	v_mfma_f32_16x16x32_bf16 v[72:75], v[136:139], v[208:211], v[72:75]
	v_lshl_add_u64 v[216:217], v[216:217], 0, s[10:11]
	v_mfma_f32_16x16x32_bf16 v[124:127], v[132:135], v[180:183], v[124:127]
	v_mfma_f32_16x16x32_bf16 v[120:123], v[140:143], v[180:183], v[120:123]
	v_lshl_add_u64 v[246:247], s[36:37], 0, v[154:155]
	v_mfma_f32_16x16x32_bf16 v[108:111], v[132:135], v[196:199], v[108:111]
	v_mfma_f32_16x16x32_bf16 v[104:107], v[140:143], v[196:199], v[104:107]
	v_lshl_add_u64 v[248:249], s[36:37], 0, v[158:159]
	v_mfma_f32_16x16x32_bf16 v[92:95], v[132:135], v[204:207], v[92:95]
	v_mfma_f32_16x16x32_bf16 v[88:91], v[140:143], v[204:207], v[88:91]
	v_lshl_add_u64 v[250:251], v[218:219], 0, s[10:11]
	v_mfma_f32_16x16x32_bf16 v[76:79], v[132:135], v[212:215], v[76:79]
	v_mfma_f32_16x16x32_bf16 v[72:75], v[140:143], v[212:215], v[72:75]
	v_lshl_add_u64 v[252:253], v[220:221], 0, s[10:11]
	v_mfma_f32_16x16x32_bf16 v[116:119], v[144:147], v[176:179], v[116:119]
	v_mfma_f32_16x16x32_bf16 v[112:115], v[168:171], v[176:179], v[112:115]
	v_mfma_f32_16x16x32_bf16 v[100:103], v[144:147], v[192:195], v[100:103]
	v_mfma_f32_16x16x32_bf16 v[96:99], v[168:171], v[192:195], v[96:99]
	v_mfma_f32_16x16x32_bf16 v[84:87], v[144:147], v[200:203], v[84:87]
	v_mfma_f32_16x16x32_bf16 v[80:83], v[168:171], v[200:203], v[80:83]
	v_mfma_f32_16x16x32_bf16 v[68:71], v[144:147], v[208:211], v[68:71]
	v_mfma_f32_16x16x32_bf16 v[64:67], v[168:171], v[208:211], v[64:67]
	v_mfma_f32_16x16x32_bf16 v[116:119], v[148:151], v[180:183], v[116:119]
	v_mfma_f32_16x16x32_bf16 v[112:115], v[172:175], v[180:183], v[112:115]
	v_mfma_f32_16x16x32_bf16 v[100:103], v[148:151], v[196:199], v[100:103]
	v_mfma_f32_16x16x32_bf16 v[96:99], v[172:175], v[196:199], v[96:99]
	v_mfma_f32_16x16x32_bf16 v[84:87], v[148:151], v[204:207], v[84:87]
	v_mfma_f32_16x16x32_bf16 v[80:83], v[172:175], v[204:207], v[80:83]
	v_mfma_f32_16x16x32_bf16 v[68:71], v[148:151], v[212:215], v[68:71]
	v_mfma_f32_16x16x32_bf16 v[64:67], v[172:175], v[212:215], v[64:67]
	s_add_i32 s38, s61, s45
	s_mov_b32 m0, s38
	s_barrier
	global_load_lds_dwordx4 v[184:185], off
	s_add_i32 m0, s38, 0x2000
	s_add_i32 s38, s62, s45
	global_load_lds_dwordx4 v[216:217], off
	s_mov_b32 m0, s38
	s_nop 0
	global_load_lds_dwordx4 v[246:247], off
	s_add_i32 m0, s38, 0x2000
	s_nop 0
	global_load_lds_dwordx4 v[248:249], off
	ds_read_b128 v[176:179], v191 offset:49152
	ds_read_b128 v[180:183], v191 offset:50176
	ds_read_b128 v[192:195], v191 offset:51200
	ds_read_b128 v[196:199], v191 offset:52224
	ds_read_b128 v[200:203], v191 offset:53248
	ds_read_b128 v[204:207], v191 offset:54272
	ds_read_b128 v[208:211], v191 offset:55296
	ds_read_b128 v[212:215], v191 offset:56320
	s_waitcnt vmcnt(6)
	s_waitcnt lgkmcnt(0)
	s_barrier
	s_waitcnt lgkmcnt(0)
	v_mfma_f32_16x16x32_bf16 v[60:63], v[128:131], v[176:179], v[60:63]
	v_mfma_f32_16x16x32_bf16 v[56:59], v[136:139], v[176:179], v[56:59]
	v_mfma_f32_16x16x32_bf16 v[44:47], v[128:131], v[192:195], v[44:47]
	v_mfma_f32_16x16x32_bf16 v[40:43], v[136:139], v[192:195], v[40:43]
	v_mfma_f32_16x16x32_bf16 v[28:31], v[128:131], v[200:203], v[28:31]
	v_mfma_f32_16x16x32_bf16 v[24:27], v[136:139], v[200:203], v[24:27]
	v_mfma_f32_16x16x32_bf16 v[12:15], v[128:131], v[208:211], v[12:15]
	v_mfma_f32_16x16x32_bf16 v[8:11], v[136:139], v[208:211], v[8:11]
	v_mfma_f32_16x16x32_bf16 v[60:63], v[132:135], v[180:183], v[60:63]
	v_mfma_f32_16x16x32_bf16 v[56:59], v[140:143], v[180:183], v[56:59]
	v_mfma_f32_16x16x32_bf16 v[44:47], v[132:135], v[196:199], v[44:47]
	v_mfma_f32_16x16x32_bf16 v[40:43], v[140:143], v[196:199], v[40:43]
	v_mfma_f32_16x16x32_bf16 v[28:31], v[132:135], v[204:207], v[28:31]
	v_mfma_f32_16x16x32_bf16 v[24:27], v[140:143], v[204:207], v[24:27]
	v_mfma_f32_16x16x32_bf16 v[12:15], v[132:135], v[212:215], v[12:15]
	v_mfma_f32_16x16x32_bf16 v[8:11], v[140:143], v[212:215], v[8:11]
	v_mfma_f32_16x16x32_bf16 v[52:55], v[144:147], v[176:179], v[52:55]
	v_mfma_f32_16x16x32_bf16 v[48:51], v[168:171], v[176:179], v[48:51]
	v_mfma_f32_16x16x32_bf16 v[36:39], v[144:147], v[192:195], v[36:39]
	v_mfma_f32_16x16x32_bf16 v[32:35], v[168:171], v[192:195], v[32:35]
	s_add_i32 s60, s60, 2
	v_mfma_f32_16x16x32_bf16 v[20:23], v[144:147], v[200:203], v[20:23]
	v_mfma_f32_16x16x32_bf16 v[16:19], v[168:171], v[200:203], v[16:19]
	s_add_u32 s34, s34, 0x100
	v_mfma_f32_16x16x32_bf16 v[4:7], v[144:147], v[208:211], v[4:7]
	v_mfma_f32_16x16x32_bf16 v[0:3], v[168:171], v[208:211], v[0:3]
	s_addc_u32 s35, s35, 0
	v_mfma_f32_16x16x32_bf16 v[52:55], v[148:151], v[180:183], v[52:55]
	v_mfma_f32_16x16x32_bf16 v[48:51], v[172:175], v[180:183], v[48:51]
	s_add_u32 s58, s58, 0x100
	v_mfma_f32_16x16x32_bf16 v[36:39], v[148:151], v[196:199], v[36:39]
	v_mfma_f32_16x16x32_bf16 v[32:35], v[172:175], v[196:199], v[32:35]
	s_addc_u32 s59, s59, 0
	v_mfma_f32_16x16x32_bf16 v[20:23], v[148:151], v[204:207], v[20:23]
	v_mfma_f32_16x16x32_bf16 v[16:19], v[172:175], v[204:207], v[16:19]
	v_mfma_f32_16x16x32_bf16 v[4:7], v[148:151], v[212:215], v[4:7]
	v_mfma_f32_16x16x32_bf16 v[0:3], v[172:175], v[212:215], v[0:3]
	s_barrier
	s_cmp_gt_u32 s60, 29
	s_cbranch_scc0 .LBB0_621
	s_and_b64 vcc, exec, s[12:13]
	s_cbranch_vccz .LBB0_624
	s_barrier

; #define PG8_STAGE(bufoff, gbase, voff) do { _Pragma("unroll") for (int _i = 0; _i < 2; ++_i) \
;         __builtin_amdgcn_global_load_lds((const unsigned*)((const char*)(gbase) + (voff)[_i]), (PG8_LAS unsigned*)(lds + (bufoff) + ldsw + _i * 8192), 16, 0, 0); } while (0)
; #define PG8_LDA(dst, b, h) do { _Pragma("unroll") for (int m = 0; m < 4; ++m) _Pragma("unroll") for (int k = 0; k < 2; ++k) dst[m][k] = *(const PG8_LAS bf16x8*)(lds + PG8_SA(b, h) + aoff + m * 2048 + k * 1024); } while (0)
; #define PG8_LDB(dst, b, h) do { _Pragma("unroll") for (int n = 0; n < 2; ++n) _Pragma("unroll") for (int k = 0; k < 2; ++k) dst[n][k] = *(const PG8_LAS bf16x8*)(lds + PG8_SB(b, h) + boff + n * 2048 + k * 1024); } while (0)
; #define PG8_MMA(ai, bj, At, Bt) do { __builtin_amdgcn_s_setprio(1); _Pragma("unroll") for (int m = 0; m < 4; ++m) _Pragma("unroll") for (int n = 0; n < 2; ++n) _Pragma("unroll") for (int k = 0; k < 2; ++k) \
;         acc[ai][bj][m][n] = __builtin_amdgcn_mfma_f32_16x16x32_bf16(Bt[n][k], At[m][k], acc[ai][bj][m][n], 0, 0, 0); __builtin_amdgcn_s_setprio(0); } while (0)
; #define PG8_WAIT_V(n) asm volatile("s_waitcnt vmcnt(" #n ")" ::: "memory")
; #define PG8_WAIT_L(n) asm volatile("s_waitcnt lgkmcnt(" #n ")" ::: "memory")
; #define PG8_BAR __builtin_amdgcn_s_barrier()
; #define PG8_SCHED __builtin_amdgcn_sched_barrier(0)
; template <class Epi, class Sched, bool ALIGN_EPI = false, bool SP2 = false>
; __device__ __forceinline__ void gemm_phase(PG8_LAS unsigned char* lds, const Gemm g, const Sched& S, const Epi& E) {
;     ...
;             PG8_LDB(B0, 0, 0); PG8_LDB(B1, 0, 1); PG8_SCHED; PG8_LDA(At, 0, 0); PG8_STAGE(PG8_SA(1, 1), a1 + hstep, voffA);
;             PG8_WAIT_V(8); PG8_WAIT_L(0); PG8_BAR; PG8_MMA(0, 0, At, B0); PG8_MMA(0, 1, At, B1); PG8_BAR; PG8_SCHED;
;             PG8_LDA(At, 0, 1); PG8_STAGE(PG8_SB(0, 0), b2, voffB); PG8_STAGE(PG8_SB(0, 1), b2 + hstep, voffB); PG8_STAGE(PG8_SA(0, 0), a2, voffA);
;             PG8_WAIT_V(8); PG8_WAIT_L(0); PG8_BAR; PG8_MMA(1, 0, At, B0); PG8_MMA(1, 1, At, B1); PG8_BAR; PG8_SCHED;
.LBB0_705:
	ds_read_b128 v[144:147], v151
	ds_read_b128 v[156:159], v151 offset:1024
	ds_read_b128 v[160:163], v151 offset:2048
	ds_read_b128 v[164:167], v151 offset:3072
	ds_read_b128 v[168:171], v152
	ds_read_b128 v[172:175], v152 offset:1024
	ds_read_b128 v[176:179], v152 offset:2048
	ds_read_b128 v[180:183], v152 offset:3072
	s_mov_b32 m0, s48
	s_nop 0
	global_load_lds_dwordx4 v[250:251], off
	s_mov_b32 m0, s49
	s_nop 0
	global_load_lds_dwordx4 v[252:253], off
	s_add_u32 s30, s28, 0xfff80080
	s_addc_u32 s31, s29, -1
	s_cmp_eq_u32 s60, 28
	s_cselect_b32 s35, s15, s31
	s_cselect_b32 s34, s56, s30
	s_cselect_b32 s31, s13, s59
	s_cselect_b32 s30, s57, s58
	v_lshl_add_u64 v[216:217], s[28:29], 0, v[136:137]
	s_add_i32 m0, s25, 0xc000
	ds_read_b128 v[184:187], v153
	ds_read_b128 v[188:191], v153 offset:1024
	ds_read_b128 v[192:195], v153 offset:2048
	ds_read_b128 v[196:199], v153 offset:3072
	ds_read_b128 v[200:203], v153 offset:4096
	ds_read_b128 v[204:207], v153 offset:5120
	ds_read_b128 v[208:211], v153 offset:6144
	ds_read_b128 v[212:215], v153 offset:7168
	global_load_lds_dwordx4 v[216:217], off
	v_lshl_add_u64 v[216:217], s[28:29], 0, v[138:139]
	s_add_i32 m0, s25, 0xe000
	s_nop 0
	global_load_lds_dwordx4 v[216:217], off
	s_waitcnt vmcnt(8)
	s_waitcnt lgkmcnt(0)
	s_barrier
	s_waitcnt lgkmcnt(0)
	v_mfma_f32_16x16x32_bf16 v[116:119], v[144:147], v[184:187], v[116:119]
	v_mfma_f32_16x16x32_bf16 v[112:115], v[160:163], v[184:187], v[112:115]
	s_add_u32 s62, s30, 0x80000
	v_mfma_f32_16x16x32_bf16 v[100:103], v[144:147], v[192:195], v[100:103]
	v_mfma_f32_16x16x32_bf16 v[96:99], v[160:163], v[192:195], v[96:99]
	s_addc_u32 s63, s31, 0
	v_mfma_f32_16x16x32_bf16 v[84:87], v[144:147], v[200:203], v[84:87]
	v_mfma_f32_16x16x32_bf16 v[80:83], v[160:163], v[200:203], v[80:83]
	v_lshl_add_u64 v[216:217], s[30:31], 0, v[132:133]
	v_mfma_f32_16x16x32_bf16 v[72:75], v[144:147], v[208:211], v[72:75]
	v_mfma_f32_16x16x32_bf16 v[68:71], v[160:163], v[208:211], v[68:71]
	v_lshl_add_u64 v[218:219], s[30:31], 0, v[128:129]
	v_mfma_f32_16x16x32_bf16 v[116:119], v[156:159], v[188:191], v[116:119]
	v_mfma_f32_16x16x32_bf16 v[112:115], v[164:167], v[188:191], v[112:115]
	v_lshl_add_u64 v[246:247], s[62:63], 0, v[132:133]
	v_mfma_f32_16x16x32_bf16 v[100:103], v[156:159], v[196:199], v[100:103]
	v_mfma_f32_16x16x32_bf16 v[96:99], v[164:167], v[196:199], v[96:99]
	v_lshl_add_u64 v[222:223], s[34:35], 0, v[130:131]
	v_mfma_f32_16x16x32_bf16 v[84:87], v[156:159], v[204:207], v[84:87]
	v_mfma_f32_16x16x32_bf16 v[80:83], v[164:167], v[204:207], v[80:83]
	v_lshl_add_u64 v[248:249], s[62:63], 0, v[128:129]
	v_mfma_f32_16x16x32_bf16 v[72:75], v[156:159], v[212:215], v[72:75]
	v_mfma_f32_16x16x32_bf16 v[68:71], v[164:167], v[212:215], v[68:71]
	v_lshl_add_u64 v[220:221], s[34:35], 0, v[134:135]
	v_mfma_f32_16x16x32_bf16 v[124:127], v[168:171], v[184:187], v[124:127]
	v_mfma_f32_16x16x32_bf16 v[120:123], v[176:179], v[184:187], v[120:123]
	v_mfma_f32_16x16x32_bf16 v[108:111], v[168:171], v[192:195], v[108:111]
	v_mfma_f32_16x16x32_bf16 v[104:107], v[176:179], v[192:195], v[104:107]
	v_mfma_f32_16x16x32_bf16 v[92:95], v[168:171], v[200:203], v[92:95]
	v_mfma_f32_16x16x32_bf16 v[88:91], v[176:179], v[200:203], v[88:91]
	v_mfma_f32_16x16x32_bf16 v[76:79], v[168:171], v[208:211], v[76:79]
	v_mfma_f32_16x16x32_bf16 v[64:67], v[176:179], v[208:211], v[64:67]
	v_mfma_f32_16x16x32_bf16 v[124:127], v[172:175], v[188:191], v[124:127]
	v_mfma_f32_16x16x32_bf16 v[120:123], v[180:183], v[188:191], v[120:123]
	v_mfma_f32_16x16x32_bf16 v[108:111], v[172:175], v[196:199], v[108:111]
	v_mfma_f32_16x16x32_bf16 v[104:107], v[180:183], v[196:199], v[104:107]
	v_mfma_f32_16x16x32_bf16 v[92:95], v[172:175], v[204:207], v[92:95]
	v_mfma_f32_16x16x32_bf16 v[88:91], v[180:183], v[204:207], v[88:91]
	v_mfma_f32_16x16x32_bf16 v[76:79], v[172:175], v[212:215], v[76:79]
	v_mfma_f32_16x16x32_bf16 v[64:67], v[180:183], v[212:215], v[64:67]
	s_add_i32 s61, s52, s42
	s_mov_b32 m0, s61
	s_barrier
	global_load_lds_dwordx4 v[216:217], off
	s_add_i32 m0, s61, 0x2000
	s_add_i32 s61, s53, s42
	global_load_lds_dwordx4 v[218:219], off
	s_mov_b32 m0, s61
	s_nop 0
	global_load_lds_dwordx4 v[246:247], off
	s_add_i32 m0, s61, 0x2000
	s_nop 0
	global_load_lds_dwordx4 v[248:249], off
	ds_read_b128 v[184:187], v153 offset:16384
	ds_read_b128 v[188:191], v153 offset:17408
	ds_read_b128 v[192:195], v153 offset:18432
	ds_read_b128 v[196:199], v153 offset:19456
	ds_read_b128 v[200:203], v153 offset:20480
	ds_read_b128 v[204:207], v153 offset:21504
	ds_read_b128 v[208:211], v153 offset:22528
	ds_read_b128 v[212:215], v153 offset:23552
	s_waitcnt vmcnt(6)
	s_waitcnt lgkmcnt(0)
	s_barrier
; #define PG8_STAGE(bufoff, gbase, voff) do { _Pragma("unroll") for (int _i = 0; _i < 2; ++_i) \
;         __builtin_amdgcn_global_load_lds((const unsigned*)((const char*)(gbase) + (voff)[_i]), (PG8_LAS unsigned*)(lds + (bufoff) + ldsw + _i * 8192), 16, 0, 0); } while (0)
; #define PG8_LDA(dst, b, h) do { _Pragma("unroll") for (int m = 0; m < 4; ++m) _Pragma("unroll") for (int k = 0; k < 2; ++k) dst[m][k] = *(const PG8_LAS bf16x8*)(lds + PG8_SA(b, h) + aoff + m * 2048 + k * 1024); } while (0)
; #define PG8_LDB(dst, b, h) do { _Pragma("unroll") for (int n = 0; n < 2; ++n) _Pragma("unroll") for (int k = 0; k < 2; ++k) dst[n][k] = *(const PG8_LAS bf16x8*)(lds + PG8_SB(b, h) + boff + n * 2048 + k * 1024); } while (0)
; #define PG8_MMA(ai, bj, At, Bt) do { __builtin_amdgcn_s_setprio(1); _Pragma("unroll") for (int m = 0; m < 4; ++m) _Pragma("unroll") for (int n = 0; n < 2; ++n) _Pragma("unroll") for (int k = 0; k < 2; ++k) \
;         acc[ai][bj][m][n] = __builtin_amdgcn_mfma_f32_16x16x32_bf16(Bt[n][k], At[m][k], acc[ai][bj][m][n], 0, 0, 0); __builtin_amdgcn_s_setprio(0); } while (0)
; #define PG8_WAIT_V(n) asm volatile("s_waitcnt vmcnt(" #n ")" ::: "memory")
; #define PG8_WAIT_L(n) asm volatile("s_waitcnt lgkmcnt(" #n ")" ::: "memory")
; #define PG8_BAR __builtin_amdgcn_s_barrier()
; #define PG8_SCHED __builtin_amdgcn_sched_barrier(0)
; template <class Epi, class Sched, bool ALIGN_EPI = false, bool SP2 = false>
; __device__ __forceinline__ void gemm_phase(PG8_LAS unsigned char* lds, const Gemm g, const Sched& S, const Epi& E) {
;     ...
;             PG8_WAIT_V(8); PG8_WAIT_L(0); PG8_BAR; PG8_MMA(1, 0, At, B0); PG8_MMA(1, 1, At, B1); PG8_BAR; PG8_SCHED;
;             PG8_LDB(B0, 1, 0); PG8_LDB(B1, 1, 1); PG8_SCHED; PG8_LDA(At, 1, 0); PG8_STAGE(PG8_SA(0, 1), a2 + hstep, voffA);
;             PG8_WAIT_V(8); PG8_WAIT_L(0); PG8_BAR; PG8_MMA(0, 0, At, B0); PG8_MMA(0, 1, At, B1); PG8_BAR; PG8_SCHED;
	s_waitcnt lgkmcnt(0)
	v_mfma_f32_16x16x32_bf16 v[56:59], v[144:147], v[184:187], v[56:59]
	v_mfma_f32_16x16x32_bf16 v[52:55], v[160:163], v[184:187], v[52:55]
	v_mfma_f32_16x16x32_bf16 v[40:43], v[144:147], v[192:195], v[40:43]
	v_mfma_f32_16x16x32_bf16 v[36:39], v[160:163], v[192:195], v[36:39]
	v_mfma_f32_16x16x32_bf16 v[24:27], v[144:147], v[200:203], v[24:27]
	v_mfma_f32_16x16x32_bf16 v[20:23], v[160:163], v[200:203], v[20:23]
	v_mfma_f32_16x16x32_bf16 v[8:11], v[144:147], v[208:211], v[8:11]
	v_mfma_f32_16x16x32_bf16 v[0:3], v[160:163], v[208:211], v[0:3]
	v_mfma_f32_16x16x32_bf16 v[56:59], v[156:159], v[188:191], v[56:59]
	v_mfma_f32_16x16x32_bf16 v[52:55], v[164:167], v[188:191], v[52:55]
	v_mfma_f32_16x16x32_bf16 v[40:43], v[156:159], v[196:199], v[40:43]
	v_mfma_f32_16x16x32_bf16 v[36:39], v[164:167], v[196:199], v[36:39]
	v_mfma_f32_16x16x32_bf16 v[24:27], v[156:159], v[204:207], v[24:27]
	v_mfma_f32_16x16x32_bf16 v[20:23], v[164:167], v[204:207], v[20:23]
	v_mfma_f32_16x16x32_bf16 v[8:11], v[156:159], v[212:215], v[8:11]
	v_mfma_f32_16x16x32_bf16 v[0:3], v[164:167], v[212:215], v[0:3]
	v_mfma_f32_16x16x32_bf16 v[60:63], v[168:171], v[184:187], v[60:63]
	v_mfma_f32_16x16x32_bf16 v[48:51], v[176:179], v[184:187], v[48:51]
	v_mfma_f32_16x16x32_bf16 v[44:47], v[168:171], v[192:195], v[44:47]
	v_mfma_f32_16x16x32_bf16 v[32:35], v[176:179], v[192:195], v[32:35]
	v_mfma_f32_16x16x32_bf16 v[28:31], v[168:171], v[200:203], v[28:31]
	v_mfma_f32_16x16x32_bf16 v[16:19], v[176:179], v[200:203], v[16:19]
	v_mfma_f32_16x16x32_bf16 v[12:15], v[168:171], v[208:211], v[12:15]
	v_mfma_f32_16x16x32_bf16 v[4:7], v[176:179], v[208:211], v[4:7]
	v_mfma_f32_16x16x32_bf16 v[60:63], v[172:175], v[188:191], v[60:63]
	v_mfma_f32_16x16x32_bf16 v[48:51], v[180:183], v[188:191], v[48:51]
	v_mfma_f32_16x16x32_bf16 v[44:47], v[172:175], v[196:199], v[44:47]
	v_mfma_f32_16x16x32_bf16 v[32:35], v[180:183], v[196:199], v[32:35]
	v_mfma_f32_16x16x32_bf16 v[28:31], v[172:175], v[204:207], v[28:31]
	v_mfma_f32_16x16x32_bf16 v[16:19], v[180:183], v[204:207], v[16:19]
	v_mfma_f32_16x16x32_bf16 v[12:15], v[172:175], v[212:215], v[12:15]
	v_mfma_f32_16x16x32_bf16 v[4:7], v[180:183], v[212:215], v[4:7]
	s_barrier
	s_add_i32 s61, 0, 0x18000
	v_add_u32_e32 v155, s61, v149
	s_add_i32 s62, 0, 0x1c000
	ds_read_b128 v[144:147], v155
	ds_read_b128 v[156:159], v155 offset:1024
	ds_read_b128 v[160:163], v155 offset:2048
	ds_read_b128 v[164:167], v155 offset:3072
	v_add_u32_e32 v155, s62, v149
	ds_read_b128 v[168:171], v155
	ds_read_b128 v[172:175], v155 offset:1024
	ds_read_b128 v[176:179], v155 offset:2048
	ds_read_b128 v[180:183], v155 offset:3072
	s_mov_b32 m0, s25
	s_nop 0
	global_load_lds_dwordx4 v[220:221], off
	s_mov_b32 m0, s45
	s_nop 0
	global_load_lds_dwordx4 v[222:223], off
	s_add_u32 s34, s34, 0x80000
	s_addc_u32 s35, s35, 0
	s_mov_b32 m0, s46
	v_lshl_add_u64 v[224:225], s[34:35], 0, v[134:135]
	ds_read_b128 v[184:187], v153 offset:32768
	ds_read_b128 v[188:191], v153 offset:33792
	ds_read_b128 v[192:195], v153 offset:34816
	ds_read_b128 v[196:199], v153 offset:35840
	ds_read_b128 v[200:203], v153 offset:36864
	ds_read_b128 v[204:207], v153 offset:37888
	ds_read_b128 v[208:211], v153 offset:38912
	ds_read_b128 v[212:215], v153 offset:39936
	global_load_lds_dwordx4 v[224:225], off
	v_lshl_add_u64 v[224:225], s[34:35], 0, v[130:131]
	s_mov_b32 m0, s47
	s_nop 0
	global_load_lds_dwordx4 v[224:225], off
	s_waitcnt vmcnt(8)
	s_waitcnt lgkmcnt(0)
	s_barrier
; #define PG8_STAGE(bufoff, gbase, voff) do { _Pragma("unroll") for (int _i = 0; _i < 2; ++_i) \
;         __builtin_amdgcn_global_load_lds((const unsigned*)((const char*)(gbase) + (voff)[_i]), (PG8_LAS unsigned*)(lds + (bufoff) + ldsw + _i * 8192), 16, 0, 0); } while (0)
; #define PG8_LDA(dst, b, h) do { _Pragma("unroll") for (int m = 0; m < 4; ++m) _Pragma("unroll") for (int k = 0; k < 2; ++k) dst[m][k] = *(const PG8_LAS bf16x8*)(lds + PG8_SA(b, h) + aoff + m * 2048 + k * 1024); } while (0)
; #define PG8_MMA(ai, bj, At, Bt) do { __builtin_amdgcn_s_setprio(1); _Pragma("unroll") for (int m = 0; m < 4; ++m) _Pragma("unroll") for (int n = 0; n < 2; ++n) _Pragma("unroll") for (int k = 0; k < 2; ++k) \
;         acc[ai][bj][m][n] = __builtin_amdgcn_mfma_f32_16x16x32_bf16(Bt[n][k], At[m][k], acc[ai][bj][m][n], 0, 0, 0); __builtin_amdgcn_s_setprio(0); } while (0)
; #define PG8_WAIT_V(n) asm volatile("s_waitcnt vmcnt(" #n ")" ::: "memory")
; #define PG8_WAIT_L(n) asm volatile("s_waitcnt lgkmcnt(" #n ")" ::: "memory")
; #define PG8_BAR __builtin_amdgcn_s_barrier()
; #define PG8_SCHED __builtin_amdgcn_sched_barrier(0)
; template <class Epi, class Sched, bool ALIGN_EPI = false, bool SP2 = false>
; __device__ __forceinline__ void gemm_phase(PG8_LAS unsigned char* lds, const Gemm g, const Sched& S, const Epi& E) {
;     ...
;         for (int t = 0; t < nt; t += 2) {
;     ...
;             PG8_WAIT_V(8); PG8_WAIT_L(0); PG8_BAR; PG8_MMA(0, 0, At, B0); PG8_MMA(0, 1, At, B1); PG8_BAR; PG8_SCHED;
;             PG8_LDA(At, 1, 1); PG8_STAGE(PG8_SB(1, 0), b3, voffB); PG8_STAGE(PG8_SB(1, 1), b3 + hstep, voffB); PG8_STAGE(PG8_SA(1, 0), a3, voffA);
;             PG8_WAIT_V(8); PG8_WAIT_L(0); PG8_BAR; PG8_MMA(1, 0, At, B0); PG8_MMA(1, 1, At, B1); PG8_BAR; PG8_SCHED;
	s_waitcnt lgkmcnt(0)
	v_mfma_f32_16x16x32_bf16 v[116:119], v[144:147], v[184:187], v[116:119]
	v_mfma_f32_16x16x32_bf16 v[112:115], v[160:163], v[184:187], v[112:115]
	s_add_u32 s30, s30, 0x80080
	v_mfma_f32_16x16x32_bf16 v[100:103], v[144:147], v[192:195], v[100:103]
	v_mfma_f32_16x16x32_bf16 v[96:99], v[160:163], v[192:195], v[96:99]
	s_addc_u32 s31, s31, 0
	v_mfma_f32_16x16x32_bf16 v[84:87], v[144:147], v[200:203], v[84:87]
	v_mfma_f32_16x16x32_bf16 v[80:83], v[160:163], v[200:203], v[80:83]
	v_lshl_add_u64 v[216:217], v[216:217], 0, s[8:9]
	v_mfma_f32_16x16x32_bf16 v[72:75], v[144:147], v[208:211], v[72:75]
	v_mfma_f32_16x16x32_bf16 v[68:71], v[160:163], v[208:211], v[68:71]
	v_lshl_add_u64 v[218:219], v[218:219], 0, s[8:9]
	v_mfma_f32_16x16x32_bf16 v[116:119], v[156:159], v[188:191], v[116:119]
	v_mfma_f32_16x16x32_bf16 v[112:115], v[164:167], v[188:191], v[112:115]
	v_lshl_add_u64 v[246:247], s[30:31], 0, v[132:133]
	v_mfma_f32_16x16x32_bf16 v[100:103], v[156:159], v[196:199], v[100:103]
	v_mfma_f32_16x16x32_bf16 v[96:99], v[164:167], v[196:199], v[96:99]
	v_lshl_add_u64 v[248:249], s[30:31], 0, v[128:129]
	v_mfma_f32_16x16x32_bf16 v[84:87], v[156:159], v[204:207], v[84:87]
	v_mfma_f32_16x16x32_bf16 v[80:83], v[164:167], v[204:207], v[80:83]
	v_lshl_add_u64 v[250:251], v[220:221], 0, s[8:9]
	v_mfma_f32_16x16x32_bf16 v[72:75], v[156:159], v[212:215], v[72:75]
	v_mfma_f32_16x16x32_bf16 v[68:71], v[164:167], v[212:215], v[68:71]
	v_lshl_add_u64 v[252:253], v[222:223], 0, s[8:9]
	v_mfma_f32_16x16x32_bf16 v[124:127], v[168:171], v[184:187], v[124:127]
	v_mfma_f32_16x16x32_bf16 v[120:123], v[176:179], v[184:187], v[120:123]
	v_mfma_f32_16x16x32_bf16 v[108:111], v[168:171], v[192:195], v[108:111]
	v_mfma_f32_16x16x32_bf16 v[104:107], v[176:179], v[192:195], v[104:107]
	v_mfma_f32_16x16x32_bf16 v[92:95], v[168:171], v[200:203], v[92:95]
	v_mfma_f32_16x16x32_bf16 v[88:91], v[176:179], v[200:203], v[88:91]
	v_mfma_f32_16x16x32_bf16 v[76:79], v[168:171], v[208:211], v[76:79]
	v_mfma_f32_16x16x32_bf16 v[64:67], v[176:179], v[208:211], v[64:67]
	v_mfma_f32_16x16x32_bf16 v[124:127], v[172:175], v[188:191], v[124:127]
	v_mfma_f32_16x16x32_bf16 v[120:123], v[180:183], v[188:191], v[120:123]
	v_mfma_f32_16x16x32_bf16 v[108:111], v[172:175], v[196:199], v[108:111]
	v_mfma_f32_16x16x32_bf16 v[104:107], v[180:183], v[196:199], v[104:107]
	v_mfma_f32_16x16x32_bf16 v[92:95], v[172:175], v[204:207], v[92:95]
	v_mfma_f32_16x16x32_bf16 v[88:91], v[180:183], v[204:207], v[88:91]
	v_mfma_f32_16x16x32_bf16 v[76:79], v[172:175], v[212:215], v[76:79]
	v_mfma_f32_16x16x32_bf16 v[64:67], v[180:183], v[212:215], v[64:67]
	s_add_i32 s34, s61, s42
	s_mov_b32 m0, s34
	s_barrier
	global_load_lds_dwordx4 v[216:217], off
	s_add_i32 m0, s34, 0x2000
	s_add_i32 s34, s62, s42
	global_load_lds_dwordx4 v[218:219], off
	s_mov_b32 m0, s34
	s_nop 0
	global_load_lds_dwordx4 v[246:247], off
	s_add_i32 m0, s34, 0x2000
	s_nop 0
	global_load_lds_dwordx4 v[248:249], off
	ds_read_b128 v[184:187], v153 offset:49152
	ds_read_b128 v[188:191], v153 offset:50176
	ds_read_b128 v[192:195], v153 offset:51200
	ds_read_b128 v[196:199], v153 offset:52224
	ds_read_b128 v[200:203], v153 offset:53248
	ds_read_b128 v[204:207], v153 offset:54272
	ds_read_b128 v[208:211], v153 offset:55296
	ds_read_b128 v[212:215], v153 offset:56320
	s_waitcnt vmcnt(6)
	s_waitcnt lgkmcnt(0)
	s_barrier
	s_waitcnt lgkmcnt(0)
	v_mfma_f32_16x16x32_bf16 v[56:59], v[144:147], v[184:187], v[56:59]
	v_mfma_f32_16x16x32_bf16 v[52:55], v[160:163], v[184:187], v[52:55]
	v_mfma_f32_16x16x32_bf16 v[40:43], v[144:147], v[192:195], v[40:43]
	v_mfma_f32_16x16x32_bf16 v[36:39], v[160:163], v[192:195], v[36:39]
	v_mfma_f32_16x16x32_bf16 v[24:27], v[144:147], v[200:203], v[24:27]
	v_mfma_f32_16x16x32_bf16 v[20:23], v[160:163], v[200:203], v[20:23]
	v_mfma_f32_16x16x32_bf16 v[8:11], v[144:147], v[208:211], v[8:11]
	v_mfma_f32_16x16x32_bf16 v[0:3], v[160:163], v[208:211], v[0:3]
	v_mfma_f32_16x16x32_bf16 v[56:59], v[156:159], v[188:191], v[56:59]
	v_mfma_f32_16x16x32_bf16 v[52:55], v[164:167], v[188:191], v[52:55]
	v_mfma_f32_16x16x32_bf16 v[40:43], v[156:159], v[196:199], v[40:43]
	v_mfma_f32_16x16x32_bf16 v[36:39], v[164:167], v[196:199], v[36:39]
	v_mfma_f32_16x16x32_bf16 v[24:27], v[156:159], v[204:207], v[24:27]
	v_mfma_f32_16x16x32_bf16 v[20:23], v[164:167], v[204:207], v[20:23]
	v_mfma_f32_16x16x32_bf16 v[8:11], v[156:159], v[212:215], v[8:11]
	v_mfma_f32_16x16x32_bf16 v[0:3], v[164:167], v[212:215], v[0:3]
	v_mfma_f32_16x16x32_bf16 v[60:63], v[168:171], v[184:187], v[60:63]
	v_mfma_f32_16x16x32_bf16 v[48:51], v[176:179], v[184:187], v[48:51]
	v_mfma_f32_16x16x32_bf16 v[44:47], v[168:171], v[192:195], v[44:47]
	v_mfma_f32_16x16x32_bf16 v[32:35], v[176:179], v[192:195], v[32:35]
	s_add_i32 s60, s60, 2
	v_mfma_f32_16x16x32_bf16 v[28:31], v[168:171], v[200:203], v[28:31]
	v_mfma_f32_16x16x32_bf16 v[16:19], v[176:179], v[200:203], v[16:19]
	s_add_u32 s28, s28, 0x100
	v_mfma_f32_16x16x32_bf16 v[12:15], v[168:171], v[208:211], v[12:15]
	v_mfma_f32_16x16x32_bf16 v[4:7], v[176:179], v[208:211], v[4:7]
	s_addc_u32 s29, s29, 0
	v_mfma_f32_16x16x32_bf16 v[60:63], v[172:175], v[188:191], v[60:63]
	v_mfma_f32_16x16x32_bf16 v[48:51], v[180:183], v[188:191], v[48:51]
	s_add_u32 s58, s58, 0x100
	v_mfma_f32_16x16x32_bf16 v[44:47], v[172:175], v[196:199], v[44:47]
	v_mfma_f32_16x16x32_bf16 v[32:35], v[180:183], v[196:199], v[32:35]
	s_addc_u32 s59, s59, 0
	v_mfma_f32_16x16x32_bf16 v[28:31], v[172:175], v[204:207], v[28:31]
	v_mfma_f32_16x16x32_bf16 v[16:19], v[180:183], v[204:207], v[16:19]
	v_mfma_f32_16x16x32_bf16 v[12:15], v[172:175], v[212:215], v[12:15]
	v_mfma_f32_16x16x32_bf16 v[4:7], v[180:183], v[212:215], v[4:7]
	s_barrier
	s_cmp_gt_u32 s60, 29
	s_cbranch_scc0 .LBB0_705
	s_and_b64 vcc, exec, s[10:11]
	s_cbranch_vccz .LBB0_708
	s_barrier

; #define PG8_STAGE(bufoff, gbase, voff) do { _Pragma("unroll") for (int _i = 0; _i < 2; ++_i) \
;         __builtin_amdgcn_global_load_lds((const unsigned*)((const char*)(gbase) + (voff)[_i]), (PG8_LAS unsigned*)(lds + (bufoff) + ldsw + _i * 8192), 16, 0, 0); } while (0)
; #define PG8_LDA(dst, b, h) do { _Pragma("unroll") for (int m = 0; m < 4; ++m) _Pragma("unroll") for (int k = 0; k < 2; ++k) dst[m][k] = *(const PG8_LAS bf16x8*)(lds + PG8_SA(b, h) + aoff + m * 2048 + k * 1024); } while (0)
; #define PG8_LDB(dst, b, h) do { _Pragma("unroll") for (int n = 0; n < 2; ++n) _Pragma("unroll") for (int k = 0; k < 2; ++k) dst[n][k] = *(const PG8_LAS bf16x8*)(lds + PG8_SB(b, h) + boff + n * 2048 + k * 1024); } while (0)
; #define PG8_MMA(ai, bj, At, Bt) do { __builtin_amdgcn_s_setprio(1); _Pragma("unroll") for (int m = 0; m < 4; ++m) _Pragma("unroll") for (int n = 0; n < 2; ++n) _Pragma("unroll") for (int k = 0; k < 2; ++k) \
;         acc[ai][bj][m][n] = __builtin_amdgcn_mfma_f32_16x16x32_bf16(Bt[n][k], At[m][k], acc[ai][bj][m][n], 0, 0, 0); __builtin_amdgcn_s_setprio(0); } while (0)
; #define PG8_WAIT_V(n) asm volatile("s_waitcnt vmcnt(" #n ")" ::: "memory")
; #define PG8_WAIT_L(n) asm volatile("s_waitcnt lgkmcnt(" #n ")" ::: "memory")
; #define PG8_BAR __builtin_amdgcn_s_barrier()
; #define PG8_SCHED __builtin_amdgcn_sched_barrier(0)
; template <class Epi, class Sched, bool ALIGN_EPI = false, bool SP2 = false>
; __device__ __forceinline__ void gemm_phase(PG8_LAS unsigned char* lds, const Gemm g, const Sched& S, const Epi& E) {
;     ...
;             PG8_LDB(B0, 0, 0); PG8_LDB(B1, 0, 1); PG8_SCHED; PG8_LDA(At, 0, 0); PG8_STAGE(PG8_SA(1, 1), a1 + hstep, voffA);
;             PG8_WAIT_V(8); PG8_WAIT_L(0); PG8_BAR; PG8_MMA(0, 0, At, B0); PG8_MMA(0, 1, At, B1); PG8_BAR; PG8_SCHED;
;             PG8_LDA(At, 0, 1); PG8_STAGE(PG8_SB(0, 0), b2, voffB); PG8_STAGE(PG8_SB(0, 1), b2 + hstep, voffB); PG8_STAGE(PG8_SA(0, 0), a2, voffA);
;             PG8_WAIT_V(8); PG8_WAIT_L(0); PG8_BAR; PG8_MMA(1, 0, At, B0); PG8_MMA(1, 1, At, B1); PG8_BAR; PG8_SCHED;
.LBB0_788:
	ds_read_b128 v[128:131], v189
	ds_read_b128 v[132:135], v189 offset:1024
	ds_read_b128 v[136:139], v189 offset:2048
	ds_read_b128 v[140:143], v189 offset:3072
	ds_read_b128 v[144:147], v190
	ds_read_b128 v[148:151], v190 offset:1024
	ds_read_b128 v[168:171], v190 offset:2048
	ds_read_b128 v[172:175], v190 offset:3072
	s_mov_b32 m0, s45
	s_nop 0
	global_load_lds_dwordx4 v[250:251], off
	s_mov_b32 m0, s46
	s_nop 0
	global_load_lds_dwordx4 v[252:253], off
	s_add_u32 s24, s22, 0x100
	s_addc_u32 s25, s23, 0
	s_cmpk_eq_i32 s58, 0x54
	s_cselect_b32 s31, s7, s25
	s_cselect_b32 s30, s6, s24
	s_cselect_b32 s29, s17, s57
	s_cselect_b32 s28, s16, s56
	v_lshl_add_u64 v[184:185], s[22:23], 0, v[160:161]
	s_add_i32 m0, s40, 0xc000
	ds_read_b128 v[176:179], v191
	ds_read_b128 v[180:183], v191 offset:1024
	ds_read_b128 v[192:195], v191 offset:2048
	ds_read_b128 v[196:199], v191 offset:3072
	ds_read_b128 v[200:203], v191 offset:4096
	ds_read_b128 v[204:207], v191 offset:5120
	ds_read_b128 v[208:211], v191 offset:6144
	ds_read_b128 v[212:215], v191 offset:7168
	global_load_lds_dwordx4 v[184:185], off
	v_lshl_add_u64 v[184:185], s[22:23], 0, v[162:163]
	s_add_i32 m0, s40, 0xe000
	s_nop 0
	global_load_lds_dwordx4 v[184:185], off
	s_waitcnt vmcnt(8)
	s_waitcnt lgkmcnt(0)
	s_barrier
	s_waitcnt lgkmcnt(0)
	v_mfma_f32_16x16x32_bf16 v[124:127], v[128:131], v[176:179], v[124:127]
	v_mfma_f32_16x16x32_bf16 v[120:123], v[136:139], v[176:179], v[120:123]
	s_add_u32 s22, s28, 0x160000
	v_mfma_f32_16x16x32_bf16 v[108:111], v[128:131], v[192:195], v[108:111]
	v_mfma_f32_16x16x32_bf16 v[104:107], v[136:139], v[192:195], v[104:107]
	s_addc_u32 s23, s29, 0
	v_mfma_f32_16x16x32_bf16 v[92:95], v[128:131], v[200:203], v[92:95]
	v_mfma_f32_16x16x32_bf16 v[88:91], v[136:139], v[200:203], v[88:91]
	v_lshl_add_u64 v[184:185], s[28:29], 0, v[154:155]
	v_mfma_f32_16x16x32_bf16 v[76:79], v[128:131], v[208:211], v[76:79]
	v_mfma_f32_16x16x32_bf16 v[72:75], v[136:139], v[208:211], v[72:75]
	v_lshl_add_u64 v[216:217], s[28:29], 0, v[158:159]
	v_mfma_f32_16x16x32_bf16 v[124:127], v[132:135], v[180:183], v[124:127]
	v_mfma_f32_16x16x32_bf16 v[120:123], v[140:143], v[180:183], v[120:123]
	v_lshl_add_u64 v[246:247], s[22:23], 0, v[154:155]
	v_mfma_f32_16x16x32_bf16 v[108:111], v[132:135], v[196:199], v[108:111]
	v_mfma_f32_16x16x32_bf16 v[104:107], v[140:143], v[196:199], v[104:107]
	v_lshl_add_u64 v[220:221], s[30:31], 0, v[156:157]
	v_mfma_f32_16x16x32_bf16 v[92:95], v[132:135], v[204:207], v[92:95]
	v_mfma_f32_16x16x32_bf16 v[88:91], v[140:143], v[204:207], v[88:91]
	v_lshl_add_u64 v[248:249], s[22:23], 0, v[158:159]
	v_mfma_f32_16x16x32_bf16 v[76:79], v[132:135], v[212:215], v[76:79]
	v_mfma_f32_16x16x32_bf16 v[72:75], v[140:143], v[212:215], v[72:75]
	v_lshl_add_u64 v[218:219], s[30:31], 0, v[152:153]
	v_mfma_f32_16x16x32_bf16 v[116:119], v[144:147], v[176:179], v[116:119]
	v_mfma_f32_16x16x32_bf16 v[112:115], v[168:171], v[176:179], v[112:115]
	v_mfma_f32_16x16x32_bf16 v[100:103], v[144:147], v[192:195], v[100:103]
	v_mfma_f32_16x16x32_bf16 v[96:99], v[168:171], v[192:195], v[96:99]
	v_mfma_f32_16x16x32_bf16 v[84:87], v[144:147], v[200:203], v[84:87]
	v_mfma_f32_16x16x32_bf16 v[80:83], v[168:171], v[200:203], v[80:83]
	v_mfma_f32_16x16x32_bf16 v[68:71], v[144:147], v[208:211], v[68:71]
	v_mfma_f32_16x16x32_bf16 v[64:67], v[168:171], v[208:211], v[64:67]
	v_mfma_f32_16x16x32_bf16 v[116:119], v[148:151], v[180:183], v[116:119]
	v_mfma_f32_16x16x32_bf16 v[112:115], v[172:175], v[180:183], v[112:115]
	v_mfma_f32_16x16x32_bf16 v[100:103], v[148:151], v[196:199], v[100:103]
	v_mfma_f32_16x16x32_bf16 v[96:99], v[172:175], v[196:199], v[96:99]
	v_mfma_f32_16x16x32_bf16 v[84:87], v[148:151], v[204:207], v[84:87]
	v_mfma_f32_16x16x32_bf16 v[80:83], v[172:175], v[204:207], v[80:83]
	v_mfma_f32_16x16x32_bf16 v[68:71], v[148:151], v[212:215], v[68:71]
	v_mfma_f32_16x16x32_bf16 v[64:67], v[172:175], v[212:215], v[64:67]
	s_add_i32 s22, s49, s39
	s_mov_b32 m0, s22
	s_barrier
	global_load_lds_dwordx4 v[184:185], off
	s_add_i32 m0, s22, 0x2000
	s_add_i32 s59, s50, s39
	global_load_lds_dwordx4 v[216:217], off
	s_mov_b32 m0, s59
	s_nop 0
	global_load_lds_dwordx4 v[246:247], off
	s_add_i32 m0, s59, 0x2000
	s_nop 0
	global_load_lds_dwordx4 v[248:249], off
	ds_read_b128 v[176:179], v191 offset:16384
	ds_read_b128 v[180:183], v191 offset:17408
	ds_read_b128 v[192:195], v191 offset:18432
	ds_read_b128 v[196:199], v191 offset:19456
	ds_read_b128 v[200:203], v191 offset:20480
	ds_read_b128 v[204:207], v191 offset:21504
	ds_read_b128 v[208:211], v191 offset:22528
	ds_read_b128 v[212:215], v191 offset:23552
	s_waitcnt vmcnt(6)
	s_waitcnt lgkmcnt(0)
	s_barrier
; #define PG8_STAGE(bufoff, gbase, voff) do { _Pragma("unroll") for (int _i = 0; _i < 2; ++_i) \
;         __builtin_amdgcn_global_load_lds((const unsigned*)((const char*)(gbase) + (voff)[_i]), (PG8_LAS unsigned*)(lds + (bufoff) + ldsw + _i * 8192), 16, 0, 0); } while (0)
; #define PG8_LDA(dst, b, h) do { _Pragma("unroll") for (int m = 0; m < 4; ++m) _Pragma("unroll") for (int k = 0; k < 2; ++k) dst[m][k] = *(const PG8_LAS bf16x8*)(lds + PG8_SA(b, h) + aoff + m * 2048 + k * 1024); } while (0)
; #define PG8_LDB(dst, b, h) do { _Pragma("unroll") for (int n = 0; n < 2; ++n) _Pragma("unroll") for (int k = 0; k < 2; ++k) dst[n][k] = *(const PG8_LAS bf16x8*)(lds + PG8_SB(b, h) + boff + n * 2048 + k * 1024); } while (0)
; #define PG8_MMA(ai, bj, At, Bt) do { __builtin_amdgcn_s_setprio(1); _Pragma("unroll") for (int m = 0; m < 4; ++m) _Pragma("unroll") for (int n = 0; n < 2; ++n) _Pragma("unroll") for (int k = 0; k < 2; ++k) \
;         acc[ai][bj][m][n] = __builtin_amdgcn_mfma_f32_16x16x32_bf16(Bt[n][k], At[m][k], acc[ai][bj][m][n], 0, 0, 0); __builtin_amdgcn_s_setprio(0); } while (0)
; #define PG8_WAIT_V(n) asm volatile("s_waitcnt vmcnt(" #n ")" ::: "memory")
; #define PG8_WAIT_L(n) asm volatile("s_waitcnt lgkmcnt(" #n ")" ::: "memory")
; #define PG8_BAR __builtin_amdgcn_s_barrier()
; #define PG8_SCHED __builtin_amdgcn_sched_barrier(0)
; template <class Epi, class Sched, bool ALIGN_EPI = false, bool SP2 = false>
; __device__ __forceinline__ void gemm_phase(PG8_LAS unsigned char* lds, const Gemm g, const Sched& S, const Epi& E) {
;     ...
;             PG8_WAIT_V(8); PG8_WAIT_L(0); PG8_BAR; PG8_MMA(1, 0, At, B0); PG8_MMA(1, 1, At, B1); PG8_BAR; PG8_SCHED;
;             PG8_LDB(B0, 1, 0); PG8_LDB(B1, 1, 1); PG8_SCHED; PG8_LDA(At, 1, 0); PG8_STAGE(PG8_SA(0, 1), a2 + hstep, voffA);
;             PG8_WAIT_V(8); PG8_WAIT_L(0); PG8_BAR; PG8_MMA(0, 0, At, B0); PG8_MMA(0, 1, At, B1); PG8_BAR; PG8_SCHED;
	s_waitcnt lgkmcnt(0)
	v_mfma_f32_16x16x32_bf16 v[60:63], v[128:131], v[176:179], v[60:63]
	v_mfma_f32_16x16x32_bf16 v[56:59], v[136:139], v[176:179], v[56:59]
	v_mfma_f32_16x16x32_bf16 v[44:47], v[128:131], v[192:195], v[44:47]
	v_mfma_f32_16x16x32_bf16 v[40:43], v[136:139], v[192:195], v[40:43]
	v_mfma_f32_16x16x32_bf16 v[28:31], v[128:131], v[200:203], v[28:31]
	v_mfma_f32_16x16x32_bf16 v[24:27], v[136:139], v[200:203], v[24:27]
	v_mfma_f32_16x16x32_bf16 v[12:15], v[128:131], v[208:211], v[12:15]
	v_mfma_f32_16x16x32_bf16 v[8:11], v[136:139], v[208:211], v[8:11]
	v_mfma_f32_16x16x32_bf16 v[60:63], v[132:135], v[180:183], v[60:63]
	v_mfma_f32_16x16x32_bf16 v[56:59], v[140:143], v[180:183], v[56:59]
	v_mfma_f32_16x16x32_bf16 v[44:47], v[132:135], v[196:199], v[44:47]
	v_mfma_f32_16x16x32_bf16 v[40:43], v[140:143], v[196:199], v[40:43]
	v_mfma_f32_16x16x32_bf16 v[28:31], v[132:135], v[204:207], v[28:31]
	v_mfma_f32_16x16x32_bf16 v[24:27], v[140:143], v[204:207], v[24:27]
	v_mfma_f32_16x16x32_bf16 v[12:15], v[132:135], v[212:215], v[12:15]
	v_mfma_f32_16x16x32_bf16 v[8:11], v[140:143], v[212:215], v[8:11]
	v_mfma_f32_16x16x32_bf16 v[52:55], v[144:147], v[176:179], v[52:55]
	v_mfma_f32_16x16x32_bf16 v[48:51], v[168:171], v[176:179], v[48:51]
	v_mfma_f32_16x16x32_bf16 v[36:39], v[144:147], v[192:195], v[36:39]
	v_mfma_f32_16x16x32_bf16 v[32:35], v[168:171], v[192:195], v[32:35]
	v_mfma_f32_16x16x32_bf16 v[20:23], v[144:147], v[200:203], v[20:23]
	v_mfma_f32_16x16x32_bf16 v[16:19], v[168:171], v[200:203], v[16:19]
	v_mfma_f32_16x16x32_bf16 v[4:7], v[144:147], v[208:211], v[4:7]
	v_mfma_f32_16x16x32_bf16 v[0:3], v[168:171], v[208:211], v[0:3]
	v_mfma_f32_16x16x32_bf16 v[52:55], v[148:151], v[180:183], v[52:55]
	v_mfma_f32_16x16x32_bf16 v[48:51], v[172:175], v[180:183], v[48:51]
	v_mfma_f32_16x16x32_bf16 v[36:39], v[148:151], v[196:199], v[36:39]
	v_mfma_f32_16x16x32_bf16 v[32:35], v[172:175], v[196:199], v[32:35]
	v_mfma_f32_16x16x32_bf16 v[20:23], v[148:151], v[204:207], v[20:23]
	v_mfma_f32_16x16x32_bf16 v[16:19], v[172:175], v[204:207], v[16:19]
	v_mfma_f32_16x16x32_bf16 v[4:7], v[148:151], v[212:215], v[4:7]
	v_mfma_f32_16x16x32_bf16 v[0:3], v[172:175], v[212:215], v[0:3]
	s_barrier
	s_add_i32 s59, 0, 0x18000
	s_add_i32 s60, 0, 0x1c000
	v_add_u32_e32 v140, s59, v187
	v_add_u32_e32 v172, s60, v187
	ds_read_b128 v[128:131], v140
	ds_read_b128 v[132:135], v140 offset:1024
	ds_read_b128 v[136:139], v140 offset:2048
	ds_read_b128 v[140:143], v140 offset:3072
	ds_read_b128 v[144:147], v172
	ds_read_b128 v[148:151], v172 offset:1024
	ds_read_b128 v[168:171], v172 offset:2048
	ds_read_b128 v[172:175], v172 offset:3072
	s_mov_b32 m0, s40
	s_nop 0
	global_load_lds_dwordx4 v[218:219], off
	s_mov_b32 m0, s41
	s_nop 0
	global_load_lds_dwordx4 v[220:221], off
	s_add_u32 s22, s30, 0x160000
	s_addc_u32 s23, s31, 0
	s_mov_b32 m0, s42
	v_lshl_add_u64 v[222:223], s[22:23], 0, v[152:153]
	ds_read_b128 v[176:179], v191 offset:32768
	ds_read_b128 v[180:183], v191 offset:33792
	ds_read_b128 v[192:195], v191 offset:34816
	ds_read_b128 v[196:199], v191 offset:35840
	ds_read_b128 v[200:203], v191 offset:36864
	ds_read_b128 v[204:207], v191 offset:37888
	ds_read_b128 v[208:211], v191 offset:38912
	ds_read_b128 v[212:215], v191 offset:39936
	global_load_lds_dwordx4 v[222:223], off
	v_lshl_add_u64 v[222:223], s[22:23], 0, v[156:157]
	s_mov_b32 m0, s43
	s_nop 0
	global_load_lds_dwordx4 v[222:223], off
	s_waitcnt vmcnt(8)
	s_waitcnt lgkmcnt(0)
	s_barrier
; #define PG8_STAGE(bufoff, gbase, voff) do { _Pragma("unroll") for (int _i = 0; _i < 2; ++_i) \
;         __builtin_amdgcn_global_load_lds((const unsigned*)((const char*)(gbase) + (voff)[_i]), (PG8_LAS unsigned*)(lds + (bufoff) + ldsw + _i * 8192), 16, 0, 0); } while (0)
; #define PG8_LDA(dst, b, h) do { _Pragma("unroll") for (int m = 0; m < 4; ++m) _Pragma("unroll") for (int k = 0; k < 2; ++k) dst[m][k] = *(const PG8_LAS bf16x8*)(lds + PG8_SA(b, h) + aoff + m * 2048 + k * 1024); } while (0)
; #define PG8_MMA(ai, bj, At, Bt) do { __builtin_amdgcn_s_setprio(1); _Pragma("unroll") for (int m = 0; m < 4; ++m) _Pragma("unroll") for (int n = 0; n < 2; ++n) _Pragma("unroll") for (int k = 0; k < 2; ++k) \
;         acc[ai][bj][m][n] = __builtin_amdgcn_mfma_f32_16x16x32_bf16(Bt[n][k], At[m][k], acc[ai][bj][m][n], 0, 0, 0); __builtin_amdgcn_s_setprio(0); } while (0)
; #define PG8_WAIT_V(n) asm volatile("s_waitcnt vmcnt(" #n ")" ::: "memory")
; #define PG8_WAIT_L(n) asm volatile("s_waitcnt lgkmcnt(" #n ")" ::: "memory")
; #define PG8_BAR __builtin_amdgcn_s_barrier()
; #define PG8_SCHED __builtin_amdgcn_sched_barrier(0)
; template <class Epi, class Sched, bool ALIGN_EPI = false, bool SP2 = false>
; __device__ __forceinline__ void gemm_phase(PG8_LAS unsigned char* lds, const Gemm g, const Sched& S, const Epi& E) {
;     ...
;         for (int t = 0; t < nt; t += 2) {
;     ...
;             PG8_WAIT_V(8); PG8_WAIT_L(0); PG8_BAR; PG8_MMA(0, 0, At, B0); PG8_MMA(0, 1, At, B1); PG8_BAR; PG8_SCHED;
;             PG8_LDA(At, 1, 1); PG8_STAGE(PG8_SB(1, 0), b3, voffB); PG8_STAGE(PG8_SB(1, 1), b3 + hstep, voffB); PG8_STAGE(PG8_SA(1, 0), a3, voffA);
;             PG8_WAIT_V(8); PG8_WAIT_L(0); PG8_BAR; PG8_MMA(1, 0, At, B0); PG8_MMA(1, 1, At, B1); PG8_BAR; PG8_SCHED;
	s_waitcnt lgkmcnt(0)
	v_mfma_f32_16x16x32_bf16 v[124:127], v[128:131], v[176:179], v[124:127]
	v_mfma_f32_16x16x32_bf16 v[120:123], v[136:139], v[176:179], v[120:123]
	s_add_u32 s22, s28, 0x160080
	v_mfma_f32_16x16x32_bf16 v[108:111], v[128:131], v[192:195], v[108:111]
	v_mfma_f32_16x16x32_bf16 v[104:107], v[136:139], v[192:195], v[104:107]
	s_addc_u32 s23, s29, 0
	v_mfma_f32_16x16x32_bf16 v[92:95], v[128:131], v[200:203], v[92:95]
	v_mfma_f32_16x16x32_bf16 v[88:91], v[136:139], v[200:203], v[88:91]
	v_lshl_add_u64 v[184:185], v[184:185], 0, s[12:13]
	v_mfma_f32_16x16x32_bf16 v[76:79], v[128:131], v[208:211], v[76:79]
	v_mfma_f32_16x16x32_bf16 v[72:75], v[136:139], v[208:211], v[72:75]
	v_lshl_add_u64 v[216:217], v[216:217], 0, s[12:13]
	v_mfma_f32_16x16x32_bf16 v[124:127], v[132:135], v[180:183], v[124:127]
	v_mfma_f32_16x16x32_bf16 v[120:123], v[140:143], v[180:183], v[120:123]
	v_lshl_add_u64 v[246:247], s[22:23], 0, v[154:155]
	v_mfma_f32_16x16x32_bf16 v[108:111], v[132:135], v[196:199], v[108:111]
	v_mfma_f32_16x16x32_bf16 v[104:107], v[140:143], v[196:199], v[104:107]
	v_lshl_add_u64 v[248:249], s[22:23], 0, v[158:159]
	v_mfma_f32_16x16x32_bf16 v[92:95], v[132:135], v[204:207], v[92:95]
	v_mfma_f32_16x16x32_bf16 v[88:91], v[140:143], v[204:207], v[88:91]
	v_lshl_add_u64 v[250:251], v[218:219], 0, s[12:13]
	v_mfma_f32_16x16x32_bf16 v[76:79], v[132:135], v[212:215], v[76:79]
	v_mfma_f32_16x16x32_bf16 v[72:75], v[140:143], v[212:215], v[72:75]
	v_lshl_add_u64 v[252:253], v[220:221], 0, s[12:13]
	v_mfma_f32_16x16x32_bf16 v[116:119], v[144:147], v[176:179], v[116:119]
	v_mfma_f32_16x16x32_bf16 v[112:115], v[168:171], v[176:179], v[112:115]
	v_mfma_f32_16x16x32_bf16 v[100:103], v[144:147], v[192:195], v[100:103]
	v_mfma_f32_16x16x32_bf16 v[96:99], v[168:171], v[192:195], v[96:99]
	v_mfma_f32_16x16x32_bf16 v[84:87], v[144:147], v[200:203], v[84:87]
	v_mfma_f32_16x16x32_bf16 v[80:83], v[168:171], v[200:203], v[80:83]
	v_mfma_f32_16x16x32_bf16 v[68:71], v[144:147], v[208:211], v[68:71]
	v_mfma_f32_16x16x32_bf16 v[64:67], v[168:171], v[208:211], v[64:67]
	v_mfma_f32_16x16x32_bf16 v[116:119], v[148:151], v[180:183], v[116:119]
	v_mfma_f32_16x16x32_bf16 v[112:115], v[172:175], v[180:183], v[112:115]
	v_mfma_f32_16x16x32_bf16 v[100:103], v[148:151], v[196:199], v[100:103]
	v_mfma_f32_16x16x32_bf16 v[96:99], v[172:175], v[196:199], v[96:99]
	v_mfma_f32_16x16x32_bf16 v[84:87], v[148:151], v[204:207], v[84:87]
	v_mfma_f32_16x16x32_bf16 v[80:83], v[172:175], v[204:207], v[80:83]
	v_mfma_f32_16x16x32_bf16 v[68:71], v[148:151], v[212:215], v[68:71]
	v_mfma_f32_16x16x32_bf16 v[64:67], v[172:175], v[212:215], v[64:67]
	s_add_i32 s22, s59, s39
	s_mov_b32 m0, s22
	s_barrier
	global_load_lds_dwordx4 v[184:185], off
	s_add_i32 m0, s22, 0x2000
	s_add_i32 s28, s60, s39
	global_load_lds_dwordx4 v[216:217], off
	s_mov_b32 m0, s28
	s_nop 0
	global_load_lds_dwordx4 v[246:247], off
	s_add_i32 m0, s28, 0x2000
	s_nop 0
	global_load_lds_dwordx4 v[248:249], off
	ds_read_b128 v[176:179], v191 offset:49152
	ds_read_b128 v[180:183], v191 offset:50176
	ds_read_b128 v[192:195], v191 offset:51200
	ds_read_b128 v[196:199], v191 offset:52224
	ds_read_b128 v[200:203], v191 offset:53248
	ds_read_b128 v[204:207], v191 offset:54272
	ds_read_b128 v[208:211], v191 offset:55296
	ds_read_b128 v[212:215], v191 offset:56320
	s_waitcnt vmcnt(6)
	s_waitcnt lgkmcnt(0)
	s_barrier
	s_waitcnt lgkmcnt(0)
	v_mfma_f32_16x16x32_bf16 v[60:63], v[128:131], v[176:179], v[60:63]
	v_mfma_f32_16x16x32_bf16 v[56:59], v[136:139], v[176:179], v[56:59]
	v_mfma_f32_16x16x32_bf16 v[44:47], v[128:131], v[192:195], v[44:47]
	v_mfma_f32_16x16x32_bf16 v[40:43], v[136:139], v[192:195], v[40:43]
	v_mfma_f32_16x16x32_bf16 v[28:31], v[128:131], v[200:203], v[28:31]
	v_mfma_f32_16x16x32_bf16 v[24:27], v[136:139], v[200:203], v[24:27]
	v_mfma_f32_16x16x32_bf16 v[12:15], v[128:131], v[208:211], v[12:15]
	v_mfma_f32_16x16x32_bf16 v[8:11], v[136:139], v[208:211], v[8:11]
	v_mfma_f32_16x16x32_bf16 v[60:63], v[132:135], v[180:183], v[60:63]
	v_mfma_f32_16x16x32_bf16 v[56:59], v[140:143], v[180:183], v[56:59]
	v_mfma_f32_16x16x32_bf16 v[44:47], v[132:135], v[196:199], v[44:47]
	v_mfma_f32_16x16x32_bf16 v[40:43], v[140:143], v[196:199], v[40:43]
	v_mfma_f32_16x16x32_bf16 v[28:31], v[132:135], v[204:207], v[28:31]
	v_mfma_f32_16x16x32_bf16 v[24:27], v[140:143], v[204:207], v[24:27]
	v_mfma_f32_16x16x32_bf16 v[12:15], v[132:135], v[212:215], v[12:15]
	v_mfma_f32_16x16x32_bf16 v[8:11], v[140:143], v[212:215], v[8:11]
	v_mfma_f32_16x16x32_bf16 v[52:55], v[144:147], v[176:179], v[52:55]
	v_mfma_f32_16x16x32_bf16 v[48:51], v[168:171], v[176:179], v[48:51]
	v_mfma_f32_16x16x32_bf16 v[36:39], v[144:147], v[192:195], v[36:39]
	v_mfma_f32_16x16x32_bf16 v[32:35], v[168:171], v[192:195], v[32:35]
	s_add_i32 s58, s58, 2
	v_mfma_f32_16x16x32_bf16 v[20:23], v[144:147], v[200:203], v[20:23]
	v_mfma_f32_16x16x32_bf16 v[16:19], v[168:171], v[200:203], v[16:19]
	s_add_u32 s56, s56, 0x100
	v_mfma_f32_16x16x32_bf16 v[4:7], v[144:147], v[208:211], v[4:7]
	v_mfma_f32_16x16x32_bf16 v[0:3], v[168:171], v[208:211], v[0:3]
	s_addc_u32 s57, s57, 0
	v_mfma_f32_16x16x32_bf16 v[52:55], v[148:151], v[180:183], v[52:55]
	v_mfma_f32_16x16x32_bf16 v[48:51], v[172:175], v[180:183], v[48:51]
	v_mfma_f32_16x16x32_bf16 v[36:39], v[148:151], v[196:199], v[36:39]
	v_mfma_f32_16x16x32_bf16 v[32:35], v[172:175], v[196:199], v[32:35]
	v_mfma_f32_16x16x32_bf16 v[20:23], v[148:151], v[204:207], v[20:23]
	v_mfma_f32_16x16x32_bf16 v[16:19], v[172:175], v[204:207], v[16:19]
	v_mfma_f32_16x16x32_bf16 v[4:7], v[148:151], v[212:215], v[4:7]
	v_mfma_f32_16x16x32_bf16 v[0:3], v[172:175], v[212:215], v[0:3]
	s_barrier
	s_cmpk_gt_u32 s58, 0x55
	s_mov_b64 s[22:23], s[24:25]
	s_cbranch_scc0 .LBB0_788
	s_and_b64 vcc, exec, s[14:15]
	s_cbranch_vccz .LBB0_791
	s_barrier
